# GEMM K-loops: first iteration peeled, accumulators start from MFMA C=0 instead of 128 v_mov zeroing per tile
# speedup vs baseline: 1.0137x; 1.0061x over previous
; #define PG8_STAGE(bufoff, gbase, voff) do { _Pragma("unroll") for (int _i = 0; _i < 2; ++_i) \
;         __builtin_amdgcn_global_load_lds((const unsigned*)((const char*)(gbase) + (voff)[_i]), (PG8_LAS unsigned*)(lds + (bufoff) + ldsw + _i * 8192), 16, 0, 0); } while (0)
; #define PG8_LDA(dst, b, h) do { _Pragma("unroll") for (int m = 0; m < 4; ++m) _Pragma("unroll") for (int k = 0; k < 2; ++k) dst[m][k] = *(const PG8_LAS bf16x8*)(lds + PG8_SA(b, h) + aoff + m * 2048 + k * 1024); } while (0)
; #define PG8_LDB(dst, b, h) do { _Pragma("unroll") for (int n = 0; n < 2; ++n) _Pragma("unroll") for (int k = 0; k < 2; ++k) dst[n][k] = *(const PG8_LAS bf16x8*)(lds + PG8_SB(b, h) + boff + n * 2048 + k * 1024); } while (0)
; #define PG8_MMA(ai, bj, At, Bt) do { __builtin_amdgcn_s_setprio(1); _Pragma("unroll") for (int m = 0; m < 4; ++m) _Pragma("unroll") for (int n = 0; n < 2; ++n) _Pragma("unroll") for (int k = 0; k < 2; ++k) \
;         acc[ai][bj][m][n] = __builtin_amdgcn_mfma_f32_16x16x32_bf16(Bt[n][k], At[m][k], acc[ai][bj][m][n], 0, 0, 0); __builtin_amdgcn_s_setprio(0); } while (0)
; #define PG8_WAIT_V(n) asm volatile("s_waitcnt vmcnt(" #n ")" ::: "memory")
; #define PG8_WAIT_L(n) asm volatile("s_waitcnt lgkmcnt(" #n ")" ::: "memory")
; template <class Epi, class Sched, bool ALIGN_EPI = false, bool SP2 = false>
; __device__ __forceinline__ void gemm_phase(PG8_LAS unsigned char* lds, const Gemm g, const Sched& S, const Epi& E) {
;     ...
;             const bool last = (t == nt - 2);
;             const char* a1 = cA + (size_t)(t + 1) * kstep;
;             const char* a2 = last ? nA : cA + (size_t)(t + 2) * kstep; const char* b2 = last ? nB : cB + (size_t)(t + 2) * kstep;
;             const char* a3 = a2 + kstep; const char* b3 = b2 + kstep;
;             if (last && has_next) S.a_ready(nxt);
;             if constexpr (SP2) {
;             PG8_LDB(B0, 0, 0); PG8_LDB(B1, 0, 1); PG8_SCHED; PG8_LDA(At, 0, 0); PG8_STAGE(PG8_SA(1, 1), a1 + hstep, voffA);
;             PG8_WAIT_V(8); PG8_WAIT_L(0); PG8_BAR; PG8_MMA(0, 0, At, B0); PG8_MMA(0, 1, At, B1); PG8_BAR; PG8_SCHED;
;             PG8_LDA(At, 0, 1); PG8_STAGE(PG8_SB(0, 0), b2, voffB); PG8_STAGE(PG8_SB(0, 1), b2 + hstep, voffB); PG8_STAGE(PG8_SA(0, 0), a2, voffA);
;             PG8_WAIT_V(8); PG8_WAIT_L(0); PG8_BAR; PG8_MMA(1, 0, At, B0); PG8_MMA(1, 1, At, B1); PG8_BAR; PG8_SCHED;
.LBB0_109:
	s_ashr_i32 s75, s74, 31
	s_lshl_b64 s[60:61], s[74:75], 19
	s_add_u32 s76, s40, s60
	s_addc_u32 s77, s41, s61
	s_and_b64 s[60:61], s[4:5], exec
	s_cselect_b32 s1, s77, s7
	s_cselect_b32 s33, s76, s6
	s_ashr_i32 s73, s72, 31
	s_lshl_b64 s[60:61], s[72:73], 19
	s_add_u32 s78, s20, s60
	s_addc_u32 s79, s21, s61
	s_and_b64 s[60:61], s[4:5], exec
	s_cselect_b32 s60, s79, s9
	s_cselect_b32 s61, s78, s8
	s_add_u32 s6, s6, 0x40080
	s_addc_u32 s7, s7, 0
	s_add_u32 s73, s8, 0x100
	s_addc_u32 s75, s9, 0
	s_mov_b32 s84, -2
	ds_read_b128 v[146:149], v160
	ds_read_b128 v[150:153], v160 offset:1024
	ds_read_b128 v[154:157], v160 offset:2048
	ds_read_b128 v[166:169], v160 offset:3072
	ds_read_b128 v[170:173], v161
	ds_read_b128 v[174:177], v161 offset:1024
	ds_read_b128 v[178:181], v161 offset:2048
	ds_read_b128 v[182:185], v161 offset:3072
	s_add_u32 s8, s6, 0xfffc0080
	s_addc_u32 s9, s7, -1
	s_cmp_eq_u32 s84, 12
	s_cselect_b32 s83, s1, s9
	s_cselect_b32 s82, s33, s8
	s_cselect_b32 s9, s60, s75
	s_cselect_b32 s8, s61, s73
	v_lshl_add_u64 v[220:221], s[6:7], 0, v[138:139]
	s_add_i32 m0, s81, 0xc000
	ds_read_b128 v[186:189], v162
	ds_read_b128 v[190:193], v162 offset:1024
	ds_read_b128 v[194:197], v162 offset:2048
	ds_read_b128 v[198:201], v162 offset:3072
	ds_read_b128 v[202:205], v162 offset:4096
	ds_read_b128 v[208:211], v162 offset:5120
	ds_read_b128 v[212:215], v162 offset:6144
	ds_read_b128 v[216:219], v162 offset:7168
	global_load_lds_dwordx4 v[220:221], off
	v_lshl_add_u64 v[220:221], s[6:7], 0, v[140:141]
	s_add_i32 m0, s81, 0xe000
	s_nop 0
	global_load_lds_dwordx4 v[220:221], off
	s_waitcnt vmcnt(8)
	s_waitcnt lgkmcnt(0)
	s_barrier
	s_setprio 1
	s_waitcnt lgkmcnt(0)
	v_mfma_f32_16x16x32_bf16 v[126:129], v[146:149], v[186:189], 0
	v_mfma_f32_16x16x32_bf16 v[122:125], v[154:157], v[186:189], 0
	v_mfma_f32_16x16x32_bf16 v[118:121], v[146:149], v[194:197], 0
	v_mfma_f32_16x16x32_bf16 v[114:117], v[154:157], v[194:197], 0
	v_mfma_f32_16x16x32_bf16 v[110:113], v[146:149], v[202:205], 0
	v_mfma_f32_16x16x32_bf16 v[106:109], v[154:157], v[202:205], 0
	v_mfma_f32_16x16x32_bf16 v[102:105], v[146:149], v[212:215], 0
	v_mfma_f32_16x16x32_bf16 v[98:101], v[154:157], v[212:215], 0
	v_mfma_f32_16x16x32_bf16 v[126:129], v[150:153], v[190:193], v[126:129]
	v_mfma_f32_16x16x32_bf16 v[122:125], v[166:169], v[190:193], v[122:125]
	v_mfma_f32_16x16x32_bf16 v[118:121], v[150:153], v[198:201], v[118:121]
	v_mfma_f32_16x16x32_bf16 v[114:117], v[166:169], v[198:201], v[114:117]
	v_mfma_f32_16x16x32_bf16 v[110:113], v[150:153], v[208:211], v[110:113]
	v_mfma_f32_16x16x32_bf16 v[106:109], v[166:169], v[208:211], v[106:109]
	v_mfma_f32_16x16x32_bf16 v[102:105], v[150:153], v[216:219], v[102:105]
	v_mfma_f32_16x16x32_bf16 v[98:101], v[166:169], v[216:219], v[98:101]
	s_setprio 0
	s_setprio 1
	v_mfma_f32_16x16x32_bf16 v[62:65], v[170:173], v[186:189], 0
	v_mfma_f32_16x16x32_bf16 v[58:61], v[178:181], v[186:189], 0
	v_mfma_f32_16x16x32_bf16 v[54:57], v[170:173], v[194:197], 0
	v_mfma_f32_16x16x32_bf16 v[50:53], v[178:181], v[194:197], 0
	v_mfma_f32_16x16x32_bf16 v[46:49], v[170:173], v[202:205], 0
	v_mfma_f32_16x16x32_bf16 v[42:45], v[178:181], v[202:205], 0
	v_mfma_f32_16x16x32_bf16 v[38:41], v[170:173], v[212:215], 0
	v_mfma_f32_16x16x32_bf16 v[34:37], v[178:181], v[212:215], 0
	v_mfma_f32_16x16x32_bf16 v[62:65], v[174:177], v[190:193], v[62:65]
	v_mfma_f32_16x16x32_bf16 v[58:61], v[182:185], v[190:193], v[58:61]
	v_mfma_f32_16x16x32_bf16 v[54:57], v[174:177], v[198:201], v[54:57]
	v_mfma_f32_16x16x32_bf16 v[50:53], v[182:185], v[198:201], v[50:53]
	v_mfma_f32_16x16x32_bf16 v[46:49], v[174:177], v[208:211], v[46:49]
	v_mfma_f32_16x16x32_bf16 v[42:45], v[182:185], v[208:211], v[42:45]
	v_mfma_f32_16x16x32_bf16 v[38:41], v[174:177], v[216:219], v[38:41]
	v_mfma_f32_16x16x32_bf16 v[34:37], v[182:185], v[216:219], v[34:37]
	s_setprio 0
	s_barrier
	s_add_i32 s85, s30, s87
	s_mov_b32 m0, s85
	ds_read_b128 v[186:189], v162 offset:16384
	ds_read_b128 v[190:193], v162 offset:17408
	ds_read_b128 v[194:197], v162 offset:18432
	ds_read_b128 v[198:201], v162 offset:19456
	ds_read_b128 v[202:205], v162 offset:20480
	ds_read_b128 v[208:211], v162 offset:21504
	ds_read_b128 v[212:215], v162 offset:22528
	ds_read_b128 v[216:219], v162 offset:23552
	global_load_lds_dwordx4 v132, s[8:9]
	s_add_i32 m0, s85, 0x2000
	s_add_u32 vcc_lo, s8, 0x40000
	v_lshl_add_u64 v[222:223], s[8:9], 0, v[136:137]
	s_addc_u32 vcc_hi, s9, 0
	s_add_i32 s85, s31, s87
	global_load_lds_dwordx4 v136, s[8:9]
	s_mov_b32 m0, s85
	v_lshl_add_u64 v[226:227], s[82:83], 0, v[134:135]
	global_load_lds_dwordx4 v132, vcc
	s_add_i32 m0, s85, 0x2000
	s_nop 0
	global_load_lds_dwordx4 v136, vcc
	v_lshl_add_u64 v[224:225], s[82:83], 0, v[130:131]
	s_mov_b32 m0, s81
	s_nop 0
	global_load_lds_dwordx4 v130, s[82:83]
	s_mov_b32 m0, s88
	s_nop 0
	global_load_lds_dwordx4 v134, s[82:83]
	s_waitcnt vmcnt(8)
	s_waitcnt lgkmcnt(0)
	s_barrier
; #define PG8_STAGE(bufoff, gbase, voff) do { _Pragma("unroll") for (int _i = 0; _i < 2; ++_i) \
;         __builtin_amdgcn_global_load_lds((const unsigned*)((const char*)(gbase) + (voff)[_i]), (PG8_LAS unsigned*)(lds + (bufoff) + ldsw + _i * 8192), 16, 0, 0); } while (0)
; #define PG8_LDA(dst, b, h) do { _Pragma("unroll") for (int m = 0; m < 4; ++m) _Pragma("unroll") for (int k = 0; k < 2; ++k) dst[m][k] = *(const PG8_LAS bf16x8*)(lds + PG8_SA(b, h) + aoff + m * 2048 + k * 1024); } while (0)
; #define PG8_LDB(dst, b, h) do { _Pragma("unroll") for (int n = 0; n < 2; ++n) _Pragma("unroll") for (int k = 0; k < 2; ++k) dst[n][k] = *(const PG8_LAS bf16x8*)(lds + PG8_SB(b, h) + boff + n * 2048 + k * 1024); } while (0)
; #define PG8_MMA(ai, bj, At, Bt) do { __builtin_amdgcn_s_setprio(1); _Pragma("unroll") for (int m = 0; m < 4; ++m) _Pragma("unroll") for (int n = 0; n < 2; ++n) _Pragma("unroll") for (int k = 0; k < 2; ++k) \
;         acc[ai][bj][m][n] = __builtin_amdgcn_mfma_f32_16x16x32_bf16(Bt[n][k], At[m][k], acc[ai][bj][m][n], 0, 0, 0); __builtin_amdgcn_s_setprio(0); } while (0)
; #define PG8_WAIT_V(n) asm volatile("s_waitcnt vmcnt(" #n ")" ::: "memory")
; #define PG8_WAIT_L(n) asm volatile("s_waitcnt lgkmcnt(" #n ")" ::: "memory")
; #define PG8_BAR __builtin_amdgcn_s_barrier()
; #define PG8_SCHED __builtin_amdgcn_sched_barrier(0)
; template <class Epi, class Sched, bool ALIGN_EPI = false, bool SP2 = false>
; __device__ __forceinline__ void gemm_phase(PG8_LAS unsigned char* lds, const Gemm g, const Sched& S, const Epi& E) {
;     ...
;             PG8_WAIT_V(8); PG8_WAIT_L(0); PG8_BAR; PG8_MMA(1, 0, At, B0); PG8_MMA(1, 1, At, B1); PG8_BAR; PG8_SCHED;
;             PG8_LDB(B0, 1, 0); PG8_LDB(B1, 1, 1); PG8_SCHED; PG8_LDA(At, 1, 0); PG8_STAGE(PG8_SA(0, 1), a2 + hstep, voffA);
;             PG8_WAIT_V(8); PG8_WAIT_L(0); PG8_BAR; PG8_MMA(0, 0, At, B0); PG8_MMA(0, 1, At, B1); PG8_BAR; PG8_SCHED;
	s_setprio 1
	s_waitcnt lgkmcnt(0)
	v_mfma_f32_16x16x32_bf16 v[94:97], v[146:149], v[186:189], 0
	v_mfma_f32_16x16x32_bf16 v[90:93], v[154:157], v[186:189], 0
	v_mfma_f32_16x16x32_bf16 v[86:89], v[146:149], v[194:197], 0
	v_mfma_f32_16x16x32_bf16 v[82:85], v[154:157], v[194:197], 0
	v_mfma_f32_16x16x32_bf16 v[78:81], v[146:149], v[202:205], 0
	v_mfma_f32_16x16x32_bf16 v[74:77], v[154:157], v[202:205], 0
	v_mfma_f32_16x16x32_bf16 v[70:73], v[146:149], v[212:215], 0
	v_mfma_f32_16x16x32_bf16 v[66:69], v[154:157], v[212:215], 0
	v_mfma_f32_16x16x32_bf16 v[94:97], v[150:153], v[190:193], v[94:97]
	v_mfma_f32_16x16x32_bf16 v[90:93], v[166:169], v[190:193], v[90:93]
	v_mfma_f32_16x16x32_bf16 v[86:89], v[150:153], v[198:201], v[86:89]
	v_mfma_f32_16x16x32_bf16 v[82:85], v[166:169], v[198:201], v[82:85]
	v_mfma_f32_16x16x32_bf16 v[78:81], v[150:153], v[208:211], v[78:81]
	v_mfma_f32_16x16x32_bf16 v[74:77], v[166:169], v[208:211], v[74:77]
	v_mfma_f32_16x16x32_bf16 v[70:73], v[150:153], v[216:219], v[70:73]
	v_mfma_f32_16x16x32_bf16 v[66:69], v[166:169], v[216:219], v[66:69]
	s_setprio 0
	s_setprio 1
	v_mfma_f32_16x16x32_bf16 v[30:33], v[170:173], v[186:189], 0
	v_mfma_f32_16x16x32_bf16 v[26:29], v[178:181], v[186:189], 0
	v_mfma_f32_16x16x32_bf16 v[22:25], v[170:173], v[194:197], 0
	v_mfma_f32_16x16x32_bf16 v[18:21], v[178:181], v[194:197], 0
	v_mfma_f32_16x16x32_bf16 v[14:17], v[170:173], v[202:205], 0
	v_mfma_f32_16x16x32_bf16 v[10:13], v[178:181], v[202:205], 0
	v_mfma_f32_16x16x32_bf16 v[6:9], v[170:173], v[212:215], 0
	v_mfma_f32_16x16x32_bf16 v[2:5], v[178:181], v[212:215], 0
	v_mfma_f32_16x16x32_bf16 v[30:33], v[174:177], v[190:193], v[30:33]
	v_mfma_f32_16x16x32_bf16 v[26:29], v[182:185], v[190:193], v[26:29]
	v_mfma_f32_16x16x32_bf16 v[22:25], v[174:177], v[198:201], v[22:25]
	v_mfma_f32_16x16x32_bf16 v[18:21], v[182:185], v[198:201], v[18:21]
	v_mfma_f32_16x16x32_bf16 v[14:17], v[174:177], v[208:211], v[14:17]
	v_mfma_f32_16x16x32_bf16 v[10:13], v[182:185], v[208:211], v[10:13]
	v_mfma_f32_16x16x32_bf16 v[6:9], v[174:177], v[216:219], v[6:9]
	v_mfma_f32_16x16x32_bf16 v[2:5], v[182:185], v[216:219], v[2:5]
	s_setprio 0
	s_barrier
	s_add_i32 s85, 0, 0x18000
	v_add_u32_e32 v165, s85, v158
	s_add_i32 vcc_lo, 0, 0x1c000
	ds_read_b128 v[146:149], v165
	ds_read_b128 v[150:153], v165 offset:1024
	ds_read_b128 v[154:157], v165 offset:2048
	ds_read_b128 v[166:169], v165 offset:3072
	v_add_u32_e32 v165, vcc_lo, v158
	ds_read_b128 v[170:173], v165
	ds_read_b128 v[174:177], v165 offset:1024
	ds_read_b128 v[178:181], v165 offset:2048
	ds_read_b128 v[182:185], v165 offset:3072
	s_add_u32 s82, s82, 0x40000
	s_addc_u32 s83, s83, 0
	s_mov_b32 m0, s89
	ds_read_b128 v[186:189], v162 offset:32768
	ds_read_b128 v[190:193], v162 offset:33792
	ds_read_b128 v[194:197], v162 offset:34816
	ds_read_b128 v[198:201], v162 offset:35840
	ds_read_b128 v[202:205], v162 offset:36864
	ds_read_b128 v[208:211], v162 offset:37888
	ds_read_b128 v[212:215], v162 offset:38912
	ds_read_b128 v[216:219], v162 offset:39936
	global_load_lds_dwordx4 v130, s[82:83]
	s_mov_b32 m0, s90
	s_nop 0
	global_load_lds_dwordx4 v134, s[82:83]
	s_waitcnt vmcnt(8)
	s_waitcnt lgkmcnt(0)
	s_barrier
	s_setprio 1
	s_waitcnt lgkmcnt(0)
	v_mfma_f32_16x16x32_bf16 v[126:129], v[146:149], v[186:189], v[126:129]
	v_mfma_f32_16x16x32_bf16 v[122:125], v[154:157], v[186:189], v[122:125]
	v_mfma_f32_16x16x32_bf16 v[118:121], v[146:149], v[194:197], v[118:121]
	v_mfma_f32_16x16x32_bf16 v[114:117], v[154:157], v[194:197], v[114:117]
	v_mfma_f32_16x16x32_bf16 v[110:113], v[146:149], v[202:205], v[110:113]
	v_mfma_f32_16x16x32_bf16 v[106:109], v[154:157], v[202:205], v[106:109]
	v_mfma_f32_16x16x32_bf16 v[102:105], v[146:149], v[212:215], v[102:105]
	v_mfma_f32_16x16x32_bf16 v[98:101], v[154:157], v[212:215], v[98:101]
	v_mfma_f32_16x16x32_bf16 v[126:129], v[150:153], v[190:193], v[126:129]
	v_mfma_f32_16x16x32_bf16 v[122:125], v[166:169], v[190:193], v[122:125]
	v_mfma_f32_16x16x32_bf16 v[118:121], v[150:153], v[198:201], v[118:121]
	v_mfma_f32_16x16x32_bf16 v[114:117], v[166:169], v[198:201], v[114:117]
	v_mfma_f32_16x16x32_bf16 v[110:113], v[150:153], v[208:211], v[110:113]
	v_mfma_f32_16x16x32_bf16 v[106:109], v[166:169], v[208:211], v[106:109]
	v_mfma_f32_16x16x32_bf16 v[102:105], v[150:153], v[216:219], v[102:105]
	v_mfma_f32_16x16x32_bf16 v[98:101], v[166:169], v[216:219], v[98:101]
	s_setprio 0
	s_setprio 1
	v_mfma_f32_16x16x32_bf16 v[62:65], v[170:173], v[186:189], v[62:65]
	v_mfma_f32_16x16x32_bf16 v[58:61], v[178:181], v[186:189], v[58:61]
	v_mfma_f32_16x16x32_bf16 v[54:57], v[170:173], v[194:197], v[54:57]
	v_mfma_f32_16x16x32_bf16 v[50:53], v[178:181], v[194:197], v[50:53]
	v_mfma_f32_16x16x32_bf16 v[46:49], v[170:173], v[202:205], v[46:49]
	v_mfma_f32_16x16x32_bf16 v[42:45], v[178:181], v[202:205], v[42:45]
	v_mfma_f32_16x16x32_bf16 v[38:41], v[170:173], v[212:215], v[38:41]
	v_mfma_f32_16x16x32_bf16 v[34:37], v[178:181], v[212:215], v[34:37]
	v_mfma_f32_16x16x32_bf16 v[62:65], v[174:177], v[190:193], v[62:65]
	v_mfma_f32_16x16x32_bf16 v[58:61], v[182:185], v[190:193], v[58:61]
	v_mfma_f32_16x16x32_bf16 v[54:57], v[174:177], v[198:201], v[54:57]
	v_mfma_f32_16x16x32_bf16 v[50:53], v[182:185], v[198:201], v[50:53]
	v_mfma_f32_16x16x32_bf16 v[46:49], v[174:177], v[208:211], v[46:49]
	v_mfma_f32_16x16x32_bf16 v[42:45], v[182:185], v[208:211], v[42:45]
	v_mfma_f32_16x16x32_bf16 v[38:41], v[174:177], v[216:219], v[38:41]
	v_mfma_f32_16x16x32_bf16 v[34:37], v[182:185], v[216:219], v[34:37]
	s_setprio 0
	s_barrier
; #define PG8_STAGE(bufoff, gbase, voff) do { _Pragma("unroll") for (int _i = 0; _i < 2; ++_i) \
;         __builtin_amdgcn_global_load_lds((const unsigned*)((const char*)(gbase) + (voff)[_i]), (PG8_LAS unsigned*)(lds + (bufoff) + ldsw + _i * 8192), 16, 0, 0); } while (0)
; #define PG8_LDA(dst, b, h) do { _Pragma("unroll") for (int m = 0; m < 4; ++m) _Pragma("unroll") for (int k = 0; k < 2; ++k) dst[m][k] = *(const PG8_LAS bf16x8*)(lds + PG8_SA(b, h) + aoff + m * 2048 + k * 1024); } while (0)
; #define PG8_MMA(ai, bj, At, Bt) do { __builtin_amdgcn_s_setprio(1); _Pragma("unroll") for (int m = 0; m < 4; ++m) _Pragma("unroll") for (int n = 0; n < 2; ++n) _Pragma("unroll") for (int k = 0; k < 2; ++k) \
;         acc[ai][bj][m][n] = __builtin_amdgcn_mfma_f32_16x16x32_bf16(Bt[n][k], At[m][k], acc[ai][bj][m][n], 0, 0, 0); __builtin_amdgcn_s_setprio(0); } while (0)
; #define PG8_WAIT_V(n) asm volatile("s_waitcnt vmcnt(" #n ")" ::: "memory")
; #define PG8_WAIT_L(n) asm volatile("s_waitcnt lgkmcnt(" #n ")" ::: "memory")
; #define PG8_BAR __builtin_amdgcn_s_barrier()
; #define PG8_SCHED __builtin_amdgcn_sched_barrier(0)
; template <class Epi, class Sched, bool ALIGN_EPI = false, bool SP2 = false>
; __device__ __forceinline__ void gemm_phase(PG8_LAS unsigned char* lds, const Gemm g, const Sched& S, const Epi& E) {
;     ...
;         for (int t = 0; t < nt; t += 2) {
;     ...
;             PG8_LDA(At, 1, 1); PG8_STAGE(PG8_SB(1, 0), b3, voffB); PG8_STAGE(PG8_SB(1, 1), b3 + hstep, voffB); PG8_STAGE(PG8_SA(1, 0), a3, voffA);
;             PG8_WAIT_V(8); PG8_WAIT_L(0); PG8_BAR; PG8_MMA(1, 0, At, B0); PG8_MMA(1, 1, At, B1); PG8_BAR; PG8_SCHED;
	s_add_i32 s82, s85, s87
	s_mov_b32 m0, s82
	ds_read_b128 v[186:189], v162 offset:49152
	ds_read_b128 v[190:193], v162 offset:50176
	ds_read_b128 v[194:197], v162 offset:51200
	ds_read_b128 v[198:201], v162 offset:52224
	ds_read_b128 v[202:205], v162 offset:53248
	ds_read_b128 v[208:211], v162 offset:54272
	ds_read_b128 v[212:215], v162 offset:55296
	ds_read_b128 v[216:219], v162 offset:56320
	s_add_u32 s98, s8, s26
	s_addc_u32 s99, s9, s27
	global_load_lds_dwordx4 v132, s[98:99]
	s_add_i32 m0, s82, 0x2000
	s_add_u32 s8, s8, 0x40080
	v_lshl_add_u64 v[220:221], v[222:223], 0, s[26:27]
	s_addc_u32 s9, s9, 0
	s_add_i32 s82, vcc_lo, s87
	global_load_lds_dwordx4 v[220:221], off
	s_mov_b32 m0, s82
	s_nop 0
	global_load_lds_dwordx4 v132, s[8:9]
	s_add_i32 m0, s82, 0x2000
	s_nop 0
	global_load_lds_dwordx4 v136, s[8:9]
	v_lshl_add_u64 v[220:221], v[224:225], 0, s[26:27]
	s_mov_b32 m0, s92
	s_nop 0
	global_load_lds_dwordx4 v[220:221], off
	v_lshl_add_u64 v[220:221], v[226:227], 0, s[26:27]
	s_mov_b32 m0, s93
	s_nop 0
	global_load_lds_dwordx4 v[220:221], off
	s_waitcnt vmcnt(8)
	s_waitcnt lgkmcnt(0)
	s_barrier
	s_setprio 1
	s_waitcnt lgkmcnt(0)
	v_mfma_f32_16x16x32_bf16 v[94:97], v[146:149], v[186:189], v[94:97]
	v_mfma_f32_16x16x32_bf16 v[90:93], v[154:157], v[186:189], v[90:93]
	v_mfma_f32_16x16x32_bf16 v[86:89], v[146:149], v[194:197], v[86:89]
	v_mfma_f32_16x16x32_bf16 v[82:85], v[154:157], v[194:197], v[82:85]
	v_mfma_f32_16x16x32_bf16 v[78:81], v[146:149], v[202:205], v[78:81]
	v_mfma_f32_16x16x32_bf16 v[74:77], v[154:157], v[202:205], v[74:77]
	v_mfma_f32_16x16x32_bf16 v[70:73], v[146:149], v[212:215], v[70:73]
	v_mfma_f32_16x16x32_bf16 v[66:69], v[154:157], v[212:215], v[66:69]
	v_mfma_f32_16x16x32_bf16 v[94:97], v[150:153], v[190:193], v[94:97]
	v_mfma_f32_16x16x32_bf16 v[90:93], v[166:169], v[190:193], v[90:93]
	v_mfma_f32_16x16x32_bf16 v[86:89], v[150:153], v[198:201], v[86:89]
	v_mfma_f32_16x16x32_bf16 v[82:85], v[166:169], v[198:201], v[82:85]
	v_mfma_f32_16x16x32_bf16 v[78:81], v[150:153], v[208:211], v[78:81]
	v_mfma_f32_16x16x32_bf16 v[74:77], v[166:169], v[208:211], v[74:77]
	v_mfma_f32_16x16x32_bf16 v[70:73], v[150:153], v[216:219], v[70:73]
	v_mfma_f32_16x16x32_bf16 v[66:69], v[166:169], v[216:219], v[66:69]
	s_setprio 0
	s_setprio 1
	v_mfma_f32_16x16x32_bf16 v[30:33], v[170:173], v[186:189], v[30:33]
	v_mfma_f32_16x16x32_bf16 v[26:29], v[178:181], v[186:189], v[26:29]
	v_mfma_f32_16x16x32_bf16 v[22:25], v[170:173], v[194:197], v[22:25]
	v_mfma_f32_16x16x32_bf16 v[18:21], v[178:181], v[194:197], v[18:21]
	v_mfma_f32_16x16x32_bf16 v[14:17], v[170:173], v[202:205], v[14:17]
	v_mfma_f32_16x16x32_bf16 v[10:13], v[178:181], v[202:205], v[10:13]
	v_mfma_f32_16x16x32_bf16 v[6:9], v[170:173], v[212:215], v[6:9]
	v_mfma_f32_16x16x32_bf16 v[2:5], v[178:181], v[212:215], v[2:5]
	v_mfma_f32_16x16x32_bf16 v[30:33], v[174:177], v[190:193], v[30:33]
	v_mfma_f32_16x16x32_bf16 v[26:29], v[182:185], v[190:193], v[26:29]
	v_mfma_f32_16x16x32_bf16 v[22:25], v[174:177], v[198:201], v[22:25]
	v_mfma_f32_16x16x32_bf16 v[18:21], v[182:185], v[198:201], v[18:21]
	v_mfma_f32_16x16x32_bf16 v[14:17], v[174:177], v[208:211], v[14:17]
	v_mfma_f32_16x16x32_bf16 v[10:13], v[182:185], v[208:211], v[10:13]
	v_mfma_f32_16x16x32_bf16 v[6:9], v[174:177], v[216:219], v[6:9]
	v_mfma_f32_16x16x32_bf16 v[2:5], v[182:185], v[216:219], v[2:5]
	s_setprio 0
	s_add_i32 s84, s84, 2
	s_add_u32 s6, s6, 0x100
	s_addc_u32 s7, s7, 0
	s_add_u32 s73, s73, 0x100
	s_addc_u32 s75, s75, 0
	s_cmp_gt_u32 s84, 13
	s_barrier

; #define PG8_STAGE(bufoff, gbase, voff) do { _Pragma("unroll") for (int _i = 0; _i < 2; ++_i) \
;         __builtin_amdgcn_global_load_lds((const unsigned*)((const char*)(gbase) + (voff)[_i]), (PG8_LAS unsigned*)(lds + (bufoff) + ldsw + _i * 8192), 16, 0, 0); } while (0)
; #define PG8_LDA(dst, b, h) do { _Pragma("unroll") for (int m = 0; m < 4; ++m) _Pragma("unroll") for (int k = 0; k < 2; ++k) dst[m][k] = *(const PG8_LAS bf16x8*)(lds + PG8_SA(b, h) + aoff + m * 2048 + k * 1024); } while (0)
; #define PG8_LDB(dst, b, h) do { _Pragma("unroll") for (int n = 0; n < 2; ++n) _Pragma("unroll") for (int k = 0; k < 2; ++k) dst[n][k] = *(const PG8_LAS bf16x8*)(lds + PG8_SB(b, h) + boff + n * 2048 + k * 1024); } while (0)
; #define PG8_MMA(ai, bj, At, Bt) do { __builtin_amdgcn_s_setprio(1); _Pragma("unroll") for (int m = 0; m < 4; ++m) _Pragma("unroll") for (int n = 0; n < 2; ++n) _Pragma("unroll") for (int k = 0; k < 2; ++k) \
;         acc[ai][bj][m][n] = __builtin_amdgcn_mfma_f32_16x16x32_bf16(Bt[n][k], At[m][k], acc[ai][bj][m][n], 0, 0, 0); __builtin_amdgcn_s_setprio(0); } while (0)
; #define PG8_WAIT_V(n) asm volatile("s_waitcnt vmcnt(" #n ")" ::: "memory")
; #define PG8_WAIT_L(n) asm volatile("s_waitcnt lgkmcnt(" #n ")" ::: "memory")
; template <class Epi, class Sched, bool ALIGN_EPI = false, bool SP2 = false>
; __device__ __forceinline__ void gemm_phase(PG8_LAS unsigned char* lds, const Gemm g, const Sched& S, const Epi& E) {
;     ...
;             const bool last = (t == nt - 2);
;             const char* a1 = cA + (size_t)(t + 1) * kstep;
;             const char* a2 = last ? nA : cA + (size_t)(t + 2) * kstep; const char* b2 = last ? nB : cB + (size_t)(t + 2) * kstep;
;             const char* a3 = a2 + kstep; const char* b3 = b2 + kstep;
;             if (last && has_next) S.a_ready(nxt);
;             if constexpr (SP2) {
;             PG8_LDB(B0, 0, 0); PG8_LDB(B1, 0, 1); PG8_SCHED; PG8_LDA(At, 0, 0); PG8_STAGE(PG8_SA(1, 1), a1 + hstep, voffA);
;             PG8_WAIT_V(8); PG8_WAIT_L(0); PG8_BAR; PG8_MMA(0, 0, At, B0); PG8_MMA(0, 1, At, B1); PG8_BAR; PG8_SCHED;
;             PG8_LDA(At, 0, 1); PG8_STAGE(PG8_SB(0, 0), b2, voffB); PG8_STAGE(PG8_SB(0, 1), b2 + hstep, voffB); PG8_STAGE(PG8_SA(0, 0), a2, voffA);
;             PG8_WAIT_V(8); PG8_WAIT_L(0); PG8_BAR; PG8_MMA(1, 0, At, B0); PG8_MMA(1, 1, At, B1); PG8_BAR; PG8_SCHED;
.LBB0_645:
	s_ashr_i32 s21, s20, 31
	s_lshl_b64 s[22:23], s[20:21], 19
	s_add_u32 s22, s0, s22
	s_addc_u32 s23, s1, s23
	s_and_b64 s[24:25], s[6:7], exec
	s_cselect_b32 s21, s23, s45
	s_cselect_b32 s27, s22, s44
	s_ashr_i32 s19, s18, 31
	s_lshl_b64 s[24:25], s[18:19], 19
	s_add_u32 s24, s64, s24
	s_addc_u32 s25, s65, s25
	s_and_b64 s[48:49], s[6:7], exec
	s_cselect_b32 s19, s25, s47
	s_cselect_b32 s33, s24, s46
	s_add_u32 s44, s44, 0x40080
	s_addc_u32 s45, s45, 0
	s_add_u32 s71, s46, 0x100
	s_addc_u32 s72, s47, 0
	s_mov_b32 s73, -2
	s_waitcnt lgkmcnt(0)
	ds_read_b128 v[148:151], v152
	ds_read_b128 v[156:159], v152 offset:1024
	ds_read_b128 v[160:163], v152 offset:2048
	ds_read_b128 v[164:167], v152 offset:3072
	ds_read_b128 v[168:171], v153
	ds_read_b128 v[172:175], v153 offset:1024
	ds_read_b128 v[176:179], v153 offset:2048
	ds_read_b128 v[180:183], v153 offset:3072
	s_add_u32 s46, s44, 0xfffc0080
	s_addc_u32 s47, s45, -1
	s_cmp_eq_u32 s73, 12
	s_cselect_b32 s49, s21, s47
	s_cselect_b32 s48, s27, s46
	s_cselect_b32 s47, s19, s72
	s_cselect_b32 s46, s33, s71
	v_lshl_add_u64 v[204:205], s[44:45], 0, v[140:141]
	s_add_i32 m0, s31, 0xc000
	ds_read_b128 v[184:187], v154
	ds_read_b128 v[188:191], v154 offset:1024
	ds_read_b128 v[192:195], v154 offset:2048
	ds_read_b128 v[196:199], v154 offset:3072
	ds_read_b128 v[200:203], v154 offset:4096
	ds_read_b128 v[208:211], v154 offset:5120
	ds_read_b128 v[212:215], v154 offset:6144
	ds_read_b128 v[216:219], v154 offset:7168
	global_load_lds_dwordx4 v[204:205], off
	v_lshl_add_u64 v[204:205], s[44:45], 0, v[142:143]
	s_add_i32 m0, s31, 0xe000
	s_nop 0
	global_load_lds_dwordx4 v[204:205], off
	s_waitcnt vmcnt(8)
	s_waitcnt lgkmcnt(0)
	s_barrier
	s_setprio 1
	s_waitcnt lgkmcnt(0)
	v_mfma_f32_16x16x32_bf16 v[126:129], v[148:151], v[184:187], 0
	v_mfma_f32_16x16x32_bf16 v[122:125], v[160:163], v[184:187], 0
	v_mfma_f32_16x16x32_bf16 v[110:113], v[148:151], v[192:195], 0
	v_mfma_f32_16x16x32_bf16 v[106:109], v[160:163], v[192:195], 0
	v_mfma_f32_16x16x32_bf16 v[94:97], v[148:151], v[200:203], 0
	v_mfma_f32_16x16x32_bf16 v[90:93], v[160:163], v[200:203], 0
	v_mfma_f32_16x16x32_bf16 v[78:81], v[148:151], v[212:215], 0
	v_mfma_f32_16x16x32_bf16 v[74:77], v[160:163], v[212:215], 0
	v_mfma_f32_16x16x32_bf16 v[126:129], v[156:159], v[188:191], v[126:129]
	v_mfma_f32_16x16x32_bf16 v[122:125], v[164:167], v[188:191], v[122:125]
	v_mfma_f32_16x16x32_bf16 v[110:113], v[156:159], v[196:199], v[110:113]
	v_mfma_f32_16x16x32_bf16 v[106:109], v[164:167], v[196:199], v[106:109]
	v_mfma_f32_16x16x32_bf16 v[94:97], v[156:159], v[208:211], v[94:97]
	v_mfma_f32_16x16x32_bf16 v[90:93], v[164:167], v[208:211], v[90:93]
	v_mfma_f32_16x16x32_bf16 v[78:81], v[156:159], v[216:219], v[78:81]
	v_mfma_f32_16x16x32_bf16 v[74:77], v[164:167], v[216:219], v[74:77]
	s_setprio 0
	s_setprio 1
	v_mfma_f32_16x16x32_bf16 v[118:121], v[168:171], v[184:187], 0
	v_mfma_f32_16x16x32_bf16 v[114:117], v[176:179], v[184:187], 0
	v_mfma_f32_16x16x32_bf16 v[102:105], v[168:171], v[192:195], 0
	v_mfma_f32_16x16x32_bf16 v[98:101], v[176:179], v[192:195], 0
	v_mfma_f32_16x16x32_bf16 v[86:89], v[168:171], v[200:203], 0
	v_mfma_f32_16x16x32_bf16 v[82:85], v[176:179], v[200:203], 0
	v_mfma_f32_16x16x32_bf16 v[70:73], v[168:171], v[212:215], 0
	v_mfma_f32_16x16x32_bf16 v[66:69], v[176:179], v[212:215], 0
	v_mfma_f32_16x16x32_bf16 v[118:121], v[172:175], v[188:191], v[118:121]
	v_mfma_f32_16x16x32_bf16 v[114:117], v[180:183], v[188:191], v[114:117]
	v_mfma_f32_16x16x32_bf16 v[102:105], v[172:175], v[196:199], v[102:105]
	v_mfma_f32_16x16x32_bf16 v[98:101], v[180:183], v[196:199], v[98:101]
	v_mfma_f32_16x16x32_bf16 v[86:89], v[172:175], v[208:211], v[86:89]
	v_mfma_f32_16x16x32_bf16 v[82:85], v[180:183], v[208:211], v[82:85]
	v_mfma_f32_16x16x32_bf16 v[70:73], v[172:175], v[216:219], v[70:73]
	v_mfma_f32_16x16x32_bf16 v[66:69], v[180:183], v[216:219], v[66:69]
	s_setprio 0
	s_barrier
	s_add_i32 s74, s68, s30
	s_mov_b32 m0, s74
	ds_read_b128 v[184:187], v154 offset:16384
	ds_read_b128 v[188:191], v154 offset:17408
	ds_read_b128 v[192:195], v154 offset:18432
	ds_read_b128 v[196:199], v154 offset:19456
	ds_read_b128 v[200:203], v154 offset:20480
	ds_read_b128 v[208:211], v154 offset:21504
	ds_read_b128 v[212:215], v154 offset:22528
	ds_read_b128 v[216:219], v154 offset:23552
	global_load_lds_dwordx4 v132, s[46:47]
	s_add_i32 m0, s74, 0x2000
	s_add_u32 s74, s46, 0x40000
	v_lshl_add_u64 v[220:221], s[46:47], 0, v[136:137]
	s_addc_u32 s75, s47, 0
	s_add_i32 s76, s69, s30
	global_load_lds_dwordx4 v136, s[46:47]
	s_mov_b32 m0, s76
	v_lshl_add_u64 v[224:225], s[48:49], 0, v[134:135]
	global_load_lds_dwordx4 v132, s[74:75]
	s_add_i32 m0, s76, 0x2000
	s_nop 0
	global_load_lds_dwordx4 v136, s[74:75]
	v_lshl_add_u64 v[222:223], s[48:49], 0, v[130:131]
	s_mov_b32 m0, s31
	s_nop 0
	global_load_lds_dwordx4 v130, s[48:49]
	s_mov_b32 m0, s50
	s_nop 0
	global_load_lds_dwordx4 v134, s[48:49]
	s_waitcnt vmcnt(8)
	s_waitcnt lgkmcnt(0)
	s_barrier
; #define PG8_STAGE(bufoff, gbase, voff) do { _Pragma("unroll") for (int _i = 0; _i < 2; ++_i) \
;         __builtin_amdgcn_global_load_lds((const unsigned*)((const char*)(gbase) + (voff)[_i]), (PG8_LAS unsigned*)(lds + (bufoff) + ldsw + _i * 8192), 16, 0, 0); } while (0)
; #define PG8_LDA(dst, b, h) do { _Pragma("unroll") for (int m = 0; m < 4; ++m) _Pragma("unroll") for (int k = 0; k < 2; ++k) dst[m][k] = *(const PG8_LAS bf16x8*)(lds + PG8_SA(b, h) + aoff + m * 2048 + k * 1024); } while (0)
; #define PG8_LDB(dst, b, h) do { _Pragma("unroll") for (int n = 0; n < 2; ++n) _Pragma("unroll") for (int k = 0; k < 2; ++k) dst[n][k] = *(const PG8_LAS bf16x8*)(lds + PG8_SB(b, h) + boff + n * 2048 + k * 1024); } while (0)
; #define PG8_MMA(ai, bj, At, Bt) do { __builtin_amdgcn_s_setprio(1); _Pragma("unroll") for (int m = 0; m < 4; ++m) _Pragma("unroll") for (int n = 0; n < 2; ++n) _Pragma("unroll") for (int k = 0; k < 2; ++k) \
;         acc[ai][bj][m][n] = __builtin_amdgcn_mfma_f32_16x16x32_bf16(Bt[n][k], At[m][k], acc[ai][bj][m][n], 0, 0, 0); __builtin_amdgcn_s_setprio(0); } while (0)
; #define PG8_WAIT_V(n) asm volatile("s_waitcnt vmcnt(" #n ")" ::: "memory")
; #define PG8_WAIT_L(n) asm volatile("s_waitcnt lgkmcnt(" #n ")" ::: "memory")
; #define PG8_BAR __builtin_amdgcn_s_barrier()
; #define PG8_SCHED __builtin_amdgcn_sched_barrier(0)
; template <class Epi, class Sched, bool ALIGN_EPI = false, bool SP2 = false>
; __device__ __forceinline__ void gemm_phase(PG8_LAS unsigned char* lds, const Gemm g, const Sched& S, const Epi& E) {
;     ...
;             PG8_WAIT_V(8); PG8_WAIT_L(0); PG8_BAR; PG8_MMA(1, 0, At, B0); PG8_MMA(1, 1, At, B1); PG8_BAR; PG8_SCHED;
;             PG8_LDB(B0, 1, 0); PG8_LDB(B1, 1, 1); PG8_SCHED; PG8_LDA(At, 1, 0); PG8_STAGE(PG8_SA(0, 1), a2 + hstep, voffA);
;             PG8_WAIT_V(8); PG8_WAIT_L(0); PG8_BAR; PG8_MMA(0, 0, At, B0); PG8_MMA(0, 1, At, B1); PG8_BAR; PG8_SCHED;
	s_setprio 1
	s_waitcnt lgkmcnt(0)
	v_mfma_f32_16x16x32_bf16 v[62:65], v[148:151], v[184:187], 0
	v_mfma_f32_16x16x32_bf16 v[58:61], v[160:163], v[184:187], 0
	v_mfma_f32_16x16x32_bf16 v[46:49], v[148:151], v[192:195], 0
	v_mfma_f32_16x16x32_bf16 v[42:45], v[160:163], v[192:195], 0
	v_mfma_f32_16x16x32_bf16 v[30:33], v[148:151], v[200:203], 0
	v_mfma_f32_16x16x32_bf16 v[26:29], v[160:163], v[200:203], 0
	v_mfma_f32_16x16x32_bf16 v[14:17], v[148:151], v[212:215], 0
	v_mfma_f32_16x16x32_bf16 v[10:13], v[160:163], v[212:215], 0
	v_mfma_f32_16x16x32_bf16 v[62:65], v[156:159], v[188:191], v[62:65]
	v_mfma_f32_16x16x32_bf16 v[58:61], v[164:167], v[188:191], v[58:61]
	v_mfma_f32_16x16x32_bf16 v[46:49], v[156:159], v[196:199], v[46:49]
	v_mfma_f32_16x16x32_bf16 v[42:45], v[164:167], v[196:199], v[42:45]
	v_mfma_f32_16x16x32_bf16 v[30:33], v[156:159], v[208:211], v[30:33]
	v_mfma_f32_16x16x32_bf16 v[26:29], v[164:167], v[208:211], v[26:29]
	v_mfma_f32_16x16x32_bf16 v[14:17], v[156:159], v[216:219], v[14:17]
	v_mfma_f32_16x16x32_bf16 v[10:13], v[164:167], v[216:219], v[10:13]
	s_setprio 0
	s_setprio 1
	v_mfma_f32_16x16x32_bf16 v[54:57], v[168:171], v[184:187], 0
	v_mfma_f32_16x16x32_bf16 v[50:53], v[176:179], v[184:187], 0
	v_mfma_f32_16x16x32_bf16 v[38:41], v[168:171], v[192:195], 0
	v_mfma_f32_16x16x32_bf16 v[34:37], v[176:179], v[192:195], 0
	v_mfma_f32_16x16x32_bf16 v[22:25], v[168:171], v[200:203], 0
	v_mfma_f32_16x16x32_bf16 v[18:21], v[176:179], v[200:203], 0
	v_mfma_f32_16x16x32_bf16 v[6:9], v[168:171], v[212:215], 0
	v_mfma_f32_16x16x32_bf16 v[2:5], v[176:179], v[212:215], 0
	v_mfma_f32_16x16x32_bf16 v[54:57], v[172:175], v[188:191], v[54:57]
	v_mfma_f32_16x16x32_bf16 v[50:53], v[180:183], v[188:191], v[50:53]
	v_mfma_f32_16x16x32_bf16 v[38:41], v[172:175], v[196:199], v[38:41]
	v_mfma_f32_16x16x32_bf16 v[34:37], v[180:183], v[196:199], v[34:37]
	v_mfma_f32_16x16x32_bf16 v[22:25], v[172:175], v[208:211], v[22:25]
	v_mfma_f32_16x16x32_bf16 v[18:21], v[180:183], v[208:211], v[18:21]
	v_mfma_f32_16x16x32_bf16 v[6:9], v[172:175], v[216:219], v[6:9]
	v_mfma_f32_16x16x32_bf16 v[2:5], v[180:183], v[216:219], v[2:5]
	s_setprio 0
	s_barrier
	s_add_i32 s74, 0, 0x18000
	s_add_i32 s75, 0, 0x1c000
	v_add_u32_e32 v164, s74, v139
	v_add_u32_e32 v180, s75, v139
	ds_read_b128 v[148:151], v164
	ds_read_b128 v[156:159], v164 offset:1024
	ds_read_b128 v[160:163], v164 offset:2048
	ds_read_b128 v[164:167], v164 offset:3072
	ds_read_b128 v[168:171], v180
	ds_read_b128 v[172:175], v180 offset:1024
	ds_read_b128 v[176:179], v180 offset:2048
	ds_read_b128 v[180:183], v180 offset:3072
	s_add_u32 s48, s48, 0x40000
	s_addc_u32 s49, s49, 0
	s_mov_b32 m0, s51
	ds_read_b128 v[184:187], v154 offset:32768
	ds_read_b128 v[188:191], v154 offset:33792
	ds_read_b128 v[192:195], v154 offset:34816
	ds_read_b128 v[196:199], v154 offset:35840
	ds_read_b128 v[200:203], v154 offset:36864
	ds_read_b128 v[208:211], v154 offset:37888
	ds_read_b128 v[212:215], v154 offset:38912
	ds_read_b128 v[216:219], v154 offset:39936
	global_load_lds_dwordx4 v130, s[48:49]
	s_mov_b32 m0, s60
	s_nop 0
	global_load_lds_dwordx4 v134, s[48:49]
	s_waitcnt vmcnt(8)
	s_waitcnt lgkmcnt(0)
	s_barrier
	s_setprio 1
	s_waitcnt lgkmcnt(0)
	v_mfma_f32_16x16x32_bf16 v[126:129], v[148:151], v[184:187], v[126:129]
	v_mfma_f32_16x16x32_bf16 v[122:125], v[160:163], v[184:187], v[122:125]
	v_mfma_f32_16x16x32_bf16 v[110:113], v[148:151], v[192:195], v[110:113]
	v_mfma_f32_16x16x32_bf16 v[106:109], v[160:163], v[192:195], v[106:109]
	v_mfma_f32_16x16x32_bf16 v[94:97], v[148:151], v[200:203], v[94:97]
	v_mfma_f32_16x16x32_bf16 v[90:93], v[160:163], v[200:203], v[90:93]
	v_mfma_f32_16x16x32_bf16 v[78:81], v[148:151], v[212:215], v[78:81]
	v_mfma_f32_16x16x32_bf16 v[74:77], v[160:163], v[212:215], v[74:77]
	v_mfma_f32_16x16x32_bf16 v[126:129], v[156:159], v[188:191], v[126:129]
	v_mfma_f32_16x16x32_bf16 v[122:125], v[164:167], v[188:191], v[122:125]
	v_mfma_f32_16x16x32_bf16 v[110:113], v[156:159], v[196:199], v[110:113]
	v_mfma_f32_16x16x32_bf16 v[106:109], v[164:167], v[196:199], v[106:109]
	v_mfma_f32_16x16x32_bf16 v[94:97], v[156:159], v[208:211], v[94:97]
	v_mfma_f32_16x16x32_bf16 v[90:93], v[164:167], v[208:211], v[90:93]
	v_mfma_f32_16x16x32_bf16 v[78:81], v[156:159], v[216:219], v[78:81]
	v_mfma_f32_16x16x32_bf16 v[74:77], v[164:167], v[216:219], v[74:77]
	s_setprio 0
	s_setprio 1
	v_mfma_f32_16x16x32_bf16 v[118:121], v[168:171], v[184:187], v[118:121]
	v_mfma_f32_16x16x32_bf16 v[114:117], v[176:179], v[184:187], v[114:117]
	v_mfma_f32_16x16x32_bf16 v[102:105], v[168:171], v[192:195], v[102:105]
	v_mfma_f32_16x16x32_bf16 v[98:101], v[176:179], v[192:195], v[98:101]
	v_mfma_f32_16x16x32_bf16 v[86:89], v[168:171], v[200:203], v[86:89]
	v_mfma_f32_16x16x32_bf16 v[82:85], v[176:179], v[200:203], v[82:85]
	v_mfma_f32_16x16x32_bf16 v[70:73], v[168:171], v[212:215], v[70:73]
	v_mfma_f32_16x16x32_bf16 v[66:69], v[176:179], v[212:215], v[66:69]
	v_mfma_f32_16x16x32_bf16 v[118:121], v[172:175], v[188:191], v[118:121]
	v_mfma_f32_16x16x32_bf16 v[114:117], v[180:183], v[188:191], v[114:117]
	v_mfma_f32_16x16x32_bf16 v[102:105], v[172:175], v[196:199], v[102:105]
	v_mfma_f32_16x16x32_bf16 v[98:101], v[180:183], v[196:199], v[98:101]
	v_mfma_f32_16x16x32_bf16 v[86:89], v[172:175], v[208:211], v[86:89]
	v_mfma_f32_16x16x32_bf16 v[82:85], v[180:183], v[208:211], v[82:85]
	v_mfma_f32_16x16x32_bf16 v[70:73], v[172:175], v[216:219], v[70:73]
	v_mfma_f32_16x16x32_bf16 v[66:69], v[180:183], v[216:219], v[66:69]
	s_setprio 0
	s_barrier
; #define PG8_STAGE(bufoff, gbase, voff) do { _Pragma("unroll") for (int _i = 0; _i < 2; ++_i) \
;         __builtin_amdgcn_global_load_lds((const unsigned*)((const char*)(gbase) + (voff)[_i]), (PG8_LAS unsigned*)(lds + (bufoff) + ldsw + _i * 8192), 16, 0, 0); } while (0)
; #define PG8_LDA(dst, b, h) do { _Pragma("unroll") for (int m = 0; m < 4; ++m) _Pragma("unroll") for (int k = 0; k < 2; ++k) dst[m][k] = *(const PG8_LAS bf16x8*)(lds + PG8_SA(b, h) + aoff + m * 2048 + k * 1024); } while (0)
; #define PG8_MMA(ai, bj, At, Bt) do { __builtin_amdgcn_s_setprio(1); _Pragma("unroll") for (int m = 0; m < 4; ++m) _Pragma("unroll") for (int n = 0; n < 2; ++n) _Pragma("unroll") for (int k = 0; k < 2; ++k) \
;         acc[ai][bj][m][n] = __builtin_amdgcn_mfma_f32_16x16x32_bf16(Bt[n][k], At[m][k], acc[ai][bj][m][n], 0, 0, 0); __builtin_amdgcn_s_setprio(0); } while (0)
; #define PG8_WAIT_V(n) asm volatile("s_waitcnt vmcnt(" #n ")" ::: "memory")
; #define PG8_WAIT_L(n) asm volatile("s_waitcnt lgkmcnt(" #n ")" ::: "memory")
; #define PG8_BAR __builtin_amdgcn_s_barrier()
; #define PG8_SCHED __builtin_amdgcn_sched_barrier(0)
; template <class Epi, class Sched, bool ALIGN_EPI = false, bool SP2 = false>
; __device__ __forceinline__ void gemm_phase(PG8_LAS unsigned char* lds, const Gemm g, const Sched& S, const Epi& E) {
;     ...
;         for (int t = 0; t < nt; t += 2) {
;     ...
;             PG8_LDA(At, 1, 1); PG8_STAGE(PG8_SB(1, 0), b3, voffB); PG8_STAGE(PG8_SB(1, 1), b3 + hstep, voffB); PG8_STAGE(PG8_SA(1, 0), a3, voffA);
;             PG8_WAIT_V(8); PG8_WAIT_L(0); PG8_BAR; PG8_MMA(1, 0, At, B0); PG8_MMA(1, 1, At, B1); PG8_BAR; PG8_SCHED;
	s_add_i32 s48, s74, s30
	s_mov_b32 m0, s48
	ds_read_b128 v[184:187], v154 offset:49152
	ds_read_b128 v[188:191], v154 offset:50176
	ds_read_b128 v[192:195], v154 offset:51200
	ds_read_b128 v[196:199], v154 offset:52224
	ds_read_b128 v[200:203], v154 offset:53248
	ds_read_b128 v[208:211], v154 offset:54272
	ds_read_b128 v[212:215], v154 offset:55296
	ds_read_b128 v[216:219], v154 offset:56320
	s_add_u32 s98, s46, s14
	s_addc_u32 s99, s47, s15
	global_load_lds_dwordx4 v132, s[98:99]
	s_add_i32 m0, s48, 0x2000
	s_add_u32 s46, s46, 0x40080
	v_lshl_add_u64 v[204:205], v[220:221], 0, s[14:15]
	s_addc_u32 s47, s47, 0
	s_add_i32 s48, s75, s30
	global_load_lds_dwordx4 v[204:205], off
	s_mov_b32 m0, s48
	s_nop 0
	global_load_lds_dwordx4 v132, s[46:47]
	s_add_i32 m0, s48, 0x2000
	s_nop 0
	global_load_lds_dwordx4 v136, s[46:47]
	v_lshl_add_u64 v[204:205], v[222:223], 0, s[14:15]
	s_mov_b32 m0, s62
	s_nop 0
	global_load_lds_dwordx4 v[204:205], off
	v_lshl_add_u64 v[204:205], v[224:225], 0, s[14:15]
	s_mov_b32 m0, s63
	s_nop 0
	global_load_lds_dwordx4 v[204:205], off
	s_waitcnt vmcnt(8)
	s_waitcnt lgkmcnt(0)
	s_barrier
	s_setprio 1
	s_waitcnt lgkmcnt(0)
	v_mfma_f32_16x16x32_bf16 v[62:65], v[148:151], v[184:187], v[62:65]
	v_mfma_f32_16x16x32_bf16 v[58:61], v[160:163], v[184:187], v[58:61]
	v_mfma_f32_16x16x32_bf16 v[46:49], v[148:151], v[192:195], v[46:49]
	v_mfma_f32_16x16x32_bf16 v[42:45], v[160:163], v[192:195], v[42:45]
	v_mfma_f32_16x16x32_bf16 v[30:33], v[148:151], v[200:203], v[30:33]
	v_mfma_f32_16x16x32_bf16 v[26:29], v[160:163], v[200:203], v[26:29]
	v_mfma_f32_16x16x32_bf16 v[14:17], v[148:151], v[212:215], v[14:17]
	v_mfma_f32_16x16x32_bf16 v[10:13], v[160:163], v[212:215], v[10:13]
	v_mfma_f32_16x16x32_bf16 v[62:65], v[156:159], v[188:191], v[62:65]
	v_mfma_f32_16x16x32_bf16 v[58:61], v[164:167], v[188:191], v[58:61]
	v_mfma_f32_16x16x32_bf16 v[46:49], v[156:159], v[196:199], v[46:49]
	v_mfma_f32_16x16x32_bf16 v[42:45], v[164:167], v[196:199], v[42:45]
	v_mfma_f32_16x16x32_bf16 v[30:33], v[156:159], v[208:211], v[30:33]
	v_mfma_f32_16x16x32_bf16 v[26:29], v[164:167], v[208:211], v[26:29]
	v_mfma_f32_16x16x32_bf16 v[14:17], v[156:159], v[216:219], v[14:17]
	v_mfma_f32_16x16x32_bf16 v[10:13], v[164:167], v[216:219], v[10:13]
	s_setprio 0
	s_setprio 1
	v_mfma_f32_16x16x32_bf16 v[54:57], v[168:171], v[184:187], v[54:57]
	v_mfma_f32_16x16x32_bf16 v[50:53], v[176:179], v[184:187], v[50:53]
	v_mfma_f32_16x16x32_bf16 v[38:41], v[168:171], v[192:195], v[38:41]
	v_mfma_f32_16x16x32_bf16 v[34:37], v[176:179], v[192:195], v[34:37]
	v_mfma_f32_16x16x32_bf16 v[22:25], v[168:171], v[200:203], v[22:25]
	v_mfma_f32_16x16x32_bf16 v[18:21], v[176:179], v[200:203], v[18:21]
	v_mfma_f32_16x16x32_bf16 v[6:9], v[168:171], v[212:215], v[6:9]
	v_mfma_f32_16x16x32_bf16 v[2:5], v[176:179], v[212:215], v[2:5]
	v_mfma_f32_16x16x32_bf16 v[54:57], v[172:175], v[188:191], v[54:57]
	v_mfma_f32_16x16x32_bf16 v[50:53], v[180:183], v[188:191], v[50:53]
	v_mfma_f32_16x16x32_bf16 v[38:41], v[172:175], v[196:199], v[38:41]
	v_mfma_f32_16x16x32_bf16 v[34:37], v[180:183], v[196:199], v[34:37]
	v_mfma_f32_16x16x32_bf16 v[22:25], v[172:175], v[208:211], v[22:25]
	v_mfma_f32_16x16x32_bf16 v[18:21], v[180:183], v[208:211], v[18:21]
	v_mfma_f32_16x16x32_bf16 v[6:9], v[172:175], v[216:219], v[6:9]
	v_mfma_f32_16x16x32_bf16 v[2:5], v[180:183], v[216:219], v[2:5]
	s_setprio 0
	s_add_i32 s73, s73, 2
	s_add_u32 s44, s44, 0x100
	s_addc_u32 s45, s45, 0
	s_add_u32 s71, s71, 0x100
	s_addc_u32 s72, s72, 0
	s_cmp_gt_u32 s73, 13
	s_barrier

; #define PG8_STAGE(bufoff, gbase, voff) do { _Pragma("unroll") for (int _i = 0; _i < 2; ++_i) \
;         __builtin_amdgcn_global_load_lds((const unsigned*)((const char*)(gbase) + (voff)[_i]), (PG8_LAS unsigned*)(lds + (bufoff) + ldsw + _i * 8192), 16, 0, 0); } while (0)
; #define PG8_LDA(dst, b, h) do { _Pragma("unroll") for (int m = 0; m < 4; ++m) _Pragma("unroll") for (int k = 0; k < 2; ++k) dst[m][k] = *(const PG8_LAS bf16x8*)(lds + PG8_SA(b, h) + aoff + m * 2048 + k * 1024); } while (0)
; #define PG8_LDB(dst, b, h) do { _Pragma("unroll") for (int n = 0; n < 2; ++n) _Pragma("unroll") for (int k = 0; k < 2; ++k) dst[n][k] = *(const PG8_LAS bf16x8*)(lds + PG8_SB(b, h) + boff + n * 2048 + k * 1024); } while (0)
; #define PG8_MMA(ai, bj, At, Bt) do { __builtin_amdgcn_s_setprio(1); _Pragma("unroll") for (int m = 0; m < 4; ++m) _Pragma("unroll") for (int n = 0; n < 2; ++n) _Pragma("unroll") for (int k = 0; k < 2; ++k) \
;         acc[ai][bj][m][n] = __builtin_amdgcn_mfma_f32_16x16x32_bf16(Bt[n][k], At[m][k], acc[ai][bj][m][n], 0, 0, 0); __builtin_amdgcn_s_setprio(0); } while (0)
; #define PG8_WAIT_V(n) asm volatile("s_waitcnt vmcnt(" #n ")" ::: "memory")
; #define PG8_WAIT_L(n) asm volatile("s_waitcnt lgkmcnt(" #n ")" ::: "memory")
; template <class Epi, class Sched, bool ALIGN_EPI = false, bool SP2 = false>
; __device__ __forceinline__ void gemm_phase(PG8_LAS unsigned char* lds, const Gemm g, const Sched& S, const Epi& E) {
;     ...
;             const bool last = (t == nt - 2);
;             const char* a1 = cA + (size_t)(t + 1) * kstep;
;             const char* a2 = last ? nA : cA + (size_t)(t + 2) * kstep; const char* b2 = last ? nB : cB + (size_t)(t + 2) * kstep;
;             const char* a3 = a2 + kstep; const char* b3 = b2 + kstep;
;             if (last && has_next) S.a_ready(nxt);
;             if constexpr (SP2) {
;             PG8_LDB(B0, 0, 0); PG8_LDB(B1, 0, 1); PG8_SCHED; PG8_LDA(At, 0, 0); PG8_STAGE(PG8_SA(1, 1), a1 + hstep, voffA);
;             PG8_WAIT_V(8); PG8_WAIT_L(0); PG8_BAR; PG8_MMA(0, 0, At, B0); PG8_MMA(0, 1, At, B1); PG8_BAR; PG8_SCHED;
;             PG8_LDA(At, 0, 1); PG8_STAGE(PG8_SB(0, 0), b2, voffB); PG8_STAGE(PG8_SB(0, 1), b2 + hstep, voffB); PG8_STAGE(PG8_SA(0, 0), a2, voffA);
;             PG8_WAIT_V(8); PG8_WAIT_L(0); PG8_BAR; PG8_MMA(1, 0, At, B0); PG8_MMA(1, 1, At, B1); PG8_BAR; PG8_SCHED;
.LBB0_739:
	s_ashr_i32 s19, s18, 31
	s_lshl_b64 s[20:21], s[18:19], 19
	s_add_u32 s20, s42, s20
	s_addc_u32 s21, s43, s21
	s_and_b64 s[22:23], s[0:1], exec
	s_cselect_b32 s19, s21, s31
	s_cselect_b32 s25, s20, s30
	s_ashr_i32 s17, s16, 31
	s_lshl_b64 s[22:23], s[16:17], 19
	s_add_u32 s22, s38, s22
	s_addc_u32 s23, s39, s23
	s_and_b64 s[44:45], s[0:1], exec
	s_cselect_b32 s17, s23, s41
	s_cselect_b32 s27, s22, s40
	s_add_u32 s30, s30, 0x40080
	s_addc_u32 s31, s31, 0
	s_add_u32 s33, s40, 0x100
	s_addc_u32 s70, s41, 0
	s_mov_b32 s71, -2
	ds_read_b128 v[156:159], v152
	ds_read_b128 v[160:163], v152 offset:1024
	ds_read_b128 v[164:167], v152 offset:2048
	ds_read_b128 v[168:171], v152 offset:3072
	ds_read_b128 v[172:175], v153
	ds_read_b128 v[176:179], v153 offset:1024
	ds_read_b128 v[180:183], v153 offset:2048
	ds_read_b128 v[184:187], v153 offset:3072
	s_add_u32 s40, s30, 0xfffc0080
	s_addc_u32 s41, s31, -1
	s_cmp_eq_u32 s71, 12
	s_cselect_b32 s45, s19, s41
	s_cselect_b32 s44, s25, s40
	s_cselect_b32 s41, s17, s70
	s_cselect_b32 s40, s27, s33
	v_lshl_add_u64 v[148:149], s[30:31], 0, v[140:141]
	s_add_i32 m0, s48, 0xc000
	ds_read_b128 v[188:191], v154
	ds_read_b128 v[192:195], v154 offset:1024
	ds_read_b128 v[196:199], v154 offset:2048
	ds_read_b128 v[200:203], v154 offset:3072
	ds_read_b128 v[208:211], v154 offset:4096
	ds_read_b128 v[212:215], v154 offset:5120
	ds_read_b128 v[216:219], v154 offset:6144
	ds_read_b128 v[220:223], v154 offset:7168
	global_load_lds_dwordx4 v[148:149], off
	v_lshl_add_u64 v[148:149], s[30:31], 0, v[142:143]
	s_add_i32 m0, s48, 0xe000
	s_nop 0
	global_load_lds_dwordx4 v[148:149], off
	s_waitcnt vmcnt(8)
	s_waitcnt lgkmcnt(0)
	s_barrier
	s_setprio 1
	s_waitcnt lgkmcnt(0)
	v_mfma_f32_16x16x32_bf16 v[126:129], v[156:159], v[188:191], 0
	v_mfma_f32_16x16x32_bf16 v[122:125], v[164:167], v[188:191], 0
	v_mfma_f32_16x16x32_bf16 v[110:113], v[156:159], v[196:199], 0
	v_mfma_f32_16x16x32_bf16 v[106:109], v[164:167], v[196:199], 0
	v_mfma_f32_16x16x32_bf16 v[94:97], v[156:159], v[208:211], 0
	v_mfma_f32_16x16x32_bf16 v[90:93], v[164:167], v[208:211], 0
	v_mfma_f32_16x16x32_bf16 v[78:81], v[156:159], v[216:219], 0
	v_mfma_f32_16x16x32_bf16 v[74:77], v[164:167], v[216:219], 0
	v_mfma_f32_16x16x32_bf16 v[126:129], v[160:163], v[192:195], v[126:129]
	v_mfma_f32_16x16x32_bf16 v[122:125], v[168:171], v[192:195], v[122:125]
	v_mfma_f32_16x16x32_bf16 v[110:113], v[160:163], v[200:203], v[110:113]
	v_mfma_f32_16x16x32_bf16 v[106:109], v[168:171], v[200:203], v[106:109]
	v_mfma_f32_16x16x32_bf16 v[94:97], v[160:163], v[212:215], v[94:97]
	v_mfma_f32_16x16x32_bf16 v[90:93], v[168:171], v[212:215], v[90:93]
	v_mfma_f32_16x16x32_bf16 v[78:81], v[160:163], v[220:223], v[78:81]
	v_mfma_f32_16x16x32_bf16 v[74:77], v[168:171], v[220:223], v[74:77]
	s_setprio 0
	s_setprio 1
	v_mfma_f32_16x16x32_bf16 v[118:121], v[172:175], v[188:191], 0
	v_mfma_f32_16x16x32_bf16 v[114:117], v[180:183], v[188:191], 0
	v_mfma_f32_16x16x32_bf16 v[102:105], v[172:175], v[196:199], 0
	v_mfma_f32_16x16x32_bf16 v[98:101], v[180:183], v[196:199], 0
	v_mfma_f32_16x16x32_bf16 v[86:89], v[172:175], v[208:211], 0
	v_mfma_f32_16x16x32_bf16 v[82:85], v[180:183], v[208:211], 0
	v_mfma_f32_16x16x32_bf16 v[70:73], v[172:175], v[216:219], 0
	v_mfma_f32_16x16x32_bf16 v[66:69], v[180:183], v[216:219], 0
	v_mfma_f32_16x16x32_bf16 v[118:121], v[176:179], v[192:195], v[118:121]
	v_mfma_f32_16x16x32_bf16 v[114:117], v[184:187], v[192:195], v[114:117]
	v_mfma_f32_16x16x32_bf16 v[102:105], v[176:179], v[200:203], v[102:105]
	v_mfma_f32_16x16x32_bf16 v[98:101], v[184:187], v[200:203], v[98:101]
	v_mfma_f32_16x16x32_bf16 v[86:89], v[176:179], v[212:215], v[86:89]
	v_mfma_f32_16x16x32_bf16 v[82:85], v[184:187], v[212:215], v[82:85]
	v_mfma_f32_16x16x32_bf16 v[70:73], v[176:179], v[220:223], v[70:73]
	v_mfma_f32_16x16x32_bf16 v[66:69], v[184:187], v[220:223], v[66:69]
	s_setprio 0
	s_barrier
	s_add_i32 s72, s66, s47
	s_mov_b32 m0, s72
	ds_read_b128 v[188:191], v154 offset:16384
	ds_read_b128 v[192:195], v154 offset:17408
	ds_read_b128 v[196:199], v154 offset:18432
	ds_read_b128 v[200:203], v154 offset:19456
	ds_read_b128 v[208:211], v154 offset:20480
	ds_read_b128 v[212:215], v154 offset:21504
	ds_read_b128 v[216:219], v154 offset:22528
	ds_read_b128 v[220:223], v154 offset:23552
	global_load_lds_dwordx4 v132, s[40:41]
	s_add_i32 m0, s72, 0x2000
	s_add_u32 s72, s40, 0x40000
	v_lshl_add_u64 v[204:205], s[40:41], 0, v[136:137]
	s_addc_u32 s73, s41, 0
	s_add_i32 s74, s67, s47
	global_load_lds_dwordx4 v136, s[40:41]
	s_mov_b32 m0, s74
	v_lshl_add_u64 v[226:227], s[44:45], 0, v[134:135]
	global_load_lds_dwordx4 v132, s[72:73]
	s_add_i32 m0, s74, 0x2000
	s_nop 0
	global_load_lds_dwordx4 v136, s[72:73]
	v_lshl_add_u64 v[224:225], s[44:45], 0, v[130:131]
	s_mov_b32 m0, s48
	s_nop 0
	global_load_lds_dwordx4 v130, s[44:45]
	s_mov_b32 m0, s49
	s_nop 0
	global_load_lds_dwordx4 v134, s[44:45]
	s_waitcnt vmcnt(8)
	s_waitcnt lgkmcnt(0)
	s_barrier
; #define PG8_STAGE(bufoff, gbase, voff) do { _Pragma("unroll") for (int _i = 0; _i < 2; ++_i) \
;         __builtin_amdgcn_global_load_lds((const unsigned*)((const char*)(gbase) + (voff)[_i]), (PG8_LAS unsigned*)(lds + (bufoff) + ldsw + _i * 8192), 16, 0, 0); } while (0)
; #define PG8_LDA(dst, b, h) do { _Pragma("unroll") for (int m = 0; m < 4; ++m) _Pragma("unroll") for (int k = 0; k < 2; ++k) dst[m][k] = *(const PG8_LAS bf16x8*)(lds + PG8_SA(b, h) + aoff + m * 2048 + k * 1024); } while (0)
; #define PG8_LDB(dst, b, h) do { _Pragma("unroll") for (int n = 0; n < 2; ++n) _Pragma("unroll") for (int k = 0; k < 2; ++k) dst[n][k] = *(const PG8_LAS bf16x8*)(lds + PG8_SB(b, h) + boff + n * 2048 + k * 1024); } while (0)
; #define PG8_MMA(ai, bj, At, Bt) do { __builtin_amdgcn_s_setprio(1); _Pragma("unroll") for (int m = 0; m < 4; ++m) _Pragma("unroll") for (int n = 0; n < 2; ++n) _Pragma("unroll") for (int k = 0; k < 2; ++k) \
;         acc[ai][bj][m][n] = __builtin_amdgcn_mfma_f32_16x16x32_bf16(Bt[n][k], At[m][k], acc[ai][bj][m][n], 0, 0, 0); __builtin_amdgcn_s_setprio(0); } while (0)
; #define PG8_WAIT_V(n) asm volatile("s_waitcnt vmcnt(" #n ")" ::: "memory")
; #define PG8_WAIT_L(n) asm volatile("s_waitcnt lgkmcnt(" #n ")" ::: "memory")
; #define PG8_BAR __builtin_amdgcn_s_barrier()
; #define PG8_SCHED __builtin_amdgcn_sched_barrier(0)
; template <class Epi, class Sched, bool ALIGN_EPI = false, bool SP2 = false>
; __device__ __forceinline__ void gemm_phase(PG8_LAS unsigned char* lds, const Gemm g, const Sched& S, const Epi& E) {
;     ...
;             PG8_WAIT_V(8); PG8_WAIT_L(0); PG8_BAR; PG8_MMA(1, 0, At, B0); PG8_MMA(1, 1, At, B1); PG8_BAR; PG8_SCHED;
;             PG8_LDB(B0, 1, 0); PG8_LDB(B1, 1, 1); PG8_SCHED; PG8_LDA(At, 1, 0); PG8_STAGE(PG8_SA(0, 1), a2 + hstep, voffA);
;             PG8_WAIT_V(8); PG8_WAIT_L(0); PG8_BAR; PG8_MMA(0, 0, At, B0); PG8_MMA(0, 1, At, B1); PG8_BAR; PG8_SCHED;
	s_setprio 1
	s_waitcnt lgkmcnt(0)
	v_mfma_f32_16x16x32_bf16 v[62:65], v[156:159], v[188:191], 0
	v_mfma_f32_16x16x32_bf16 v[58:61], v[164:167], v[188:191], 0
	v_mfma_f32_16x16x32_bf16 v[46:49], v[156:159], v[196:199], 0
	v_mfma_f32_16x16x32_bf16 v[42:45], v[164:167], v[196:199], 0
	v_mfma_f32_16x16x32_bf16 v[30:33], v[156:159], v[208:211], 0
	v_mfma_f32_16x16x32_bf16 v[26:29], v[164:167], v[208:211], 0
	v_mfma_f32_16x16x32_bf16 v[14:17], v[156:159], v[216:219], 0
	v_mfma_f32_16x16x32_bf16 v[10:13], v[164:167], v[216:219], 0
	v_mfma_f32_16x16x32_bf16 v[62:65], v[160:163], v[192:195], v[62:65]
	v_mfma_f32_16x16x32_bf16 v[58:61], v[168:171], v[192:195], v[58:61]
	v_mfma_f32_16x16x32_bf16 v[46:49], v[160:163], v[200:203], v[46:49]
	v_mfma_f32_16x16x32_bf16 v[42:45], v[168:171], v[200:203], v[42:45]
	v_mfma_f32_16x16x32_bf16 v[30:33], v[160:163], v[212:215], v[30:33]
	v_mfma_f32_16x16x32_bf16 v[26:29], v[168:171], v[212:215], v[26:29]
	v_mfma_f32_16x16x32_bf16 v[14:17], v[160:163], v[220:223], v[14:17]
	v_mfma_f32_16x16x32_bf16 v[10:13], v[168:171], v[220:223], v[10:13]
	s_setprio 0
	s_setprio 1
	v_mfma_f32_16x16x32_bf16 v[54:57], v[172:175], v[188:191], 0
	v_mfma_f32_16x16x32_bf16 v[50:53], v[180:183], v[188:191], 0
	v_mfma_f32_16x16x32_bf16 v[38:41], v[172:175], v[196:199], 0
	v_mfma_f32_16x16x32_bf16 v[34:37], v[180:183], v[196:199], 0
	v_mfma_f32_16x16x32_bf16 v[22:25], v[172:175], v[208:211], 0
	v_mfma_f32_16x16x32_bf16 v[18:21], v[180:183], v[208:211], 0
	v_mfma_f32_16x16x32_bf16 v[6:9], v[172:175], v[216:219], 0
	v_mfma_f32_16x16x32_bf16 v[2:5], v[180:183], v[216:219], 0
	v_mfma_f32_16x16x32_bf16 v[54:57], v[176:179], v[192:195], v[54:57]
	v_mfma_f32_16x16x32_bf16 v[50:53], v[184:187], v[192:195], v[50:53]
	v_mfma_f32_16x16x32_bf16 v[38:41], v[176:179], v[200:203], v[38:41]
	v_mfma_f32_16x16x32_bf16 v[34:37], v[184:187], v[200:203], v[34:37]
	v_mfma_f32_16x16x32_bf16 v[22:25], v[176:179], v[212:215], v[22:25]
	v_mfma_f32_16x16x32_bf16 v[18:21], v[184:187], v[212:215], v[18:21]
	v_mfma_f32_16x16x32_bf16 v[6:9], v[176:179], v[220:223], v[6:9]
	v_mfma_f32_16x16x32_bf16 v[2:5], v[184:187], v[220:223], v[2:5]
	s_setprio 0
	s_barrier
	s_add_i32 s72, 0, 0x18000
	v_add_u32_e32 v150, s72, v151
	s_add_i32 s73, 0, 0x1c000
	ds_read_b128 v[156:159], v150
	ds_read_b128 v[160:163], v150 offset:1024
	ds_read_b128 v[164:167], v150 offset:2048
	ds_read_b128 v[168:171], v150 offset:3072
	v_add_u32_e32 v150, s73, v151
	ds_read_b128 v[172:175], v150
	ds_read_b128 v[176:179], v150 offset:1024
	ds_read_b128 v[180:183], v150 offset:2048
	ds_read_b128 v[184:187], v150 offset:3072
	s_add_u32 s44, s44, 0x40000
	s_addc_u32 s45, s45, 0
	s_mov_b32 m0, s50
	ds_read_b128 v[188:191], v154 offset:32768
	ds_read_b128 v[192:195], v154 offset:33792
	ds_read_b128 v[196:199], v154 offset:34816
	ds_read_b128 v[200:203], v154 offset:35840
	ds_read_b128 v[208:211], v154 offset:36864
	ds_read_b128 v[212:215], v154 offset:37888
	ds_read_b128 v[216:219], v154 offset:38912
	ds_read_b128 v[220:223], v154 offset:39936
	global_load_lds_dwordx4 v130, s[44:45]
	s_mov_b32 m0, s51
	s_nop 0
	global_load_lds_dwordx4 v134, s[44:45]
	s_waitcnt vmcnt(8)
	s_waitcnt lgkmcnt(0)
	s_barrier
	s_setprio 1
	s_waitcnt lgkmcnt(0)
	v_mfma_f32_16x16x32_bf16 v[126:129], v[156:159], v[188:191], v[126:129]
	v_mfma_f32_16x16x32_bf16 v[122:125], v[164:167], v[188:191], v[122:125]
	v_mfma_f32_16x16x32_bf16 v[110:113], v[156:159], v[196:199], v[110:113]
	v_mfma_f32_16x16x32_bf16 v[106:109], v[164:167], v[196:199], v[106:109]
	v_mfma_f32_16x16x32_bf16 v[94:97], v[156:159], v[208:211], v[94:97]
	v_mfma_f32_16x16x32_bf16 v[90:93], v[164:167], v[208:211], v[90:93]
	v_mfma_f32_16x16x32_bf16 v[78:81], v[156:159], v[216:219], v[78:81]
	v_mfma_f32_16x16x32_bf16 v[74:77], v[164:167], v[216:219], v[74:77]
	v_mfma_f32_16x16x32_bf16 v[126:129], v[160:163], v[192:195], v[126:129]
	v_mfma_f32_16x16x32_bf16 v[122:125], v[168:171], v[192:195], v[122:125]
	v_mfma_f32_16x16x32_bf16 v[110:113], v[160:163], v[200:203], v[110:113]
	v_mfma_f32_16x16x32_bf16 v[106:109], v[168:171], v[200:203], v[106:109]
	v_mfma_f32_16x16x32_bf16 v[94:97], v[160:163], v[212:215], v[94:97]
	v_mfma_f32_16x16x32_bf16 v[90:93], v[168:171], v[212:215], v[90:93]
	v_mfma_f32_16x16x32_bf16 v[78:81], v[160:163], v[220:223], v[78:81]
	v_mfma_f32_16x16x32_bf16 v[74:77], v[168:171], v[220:223], v[74:77]
	s_setprio 0
	s_setprio 1
	v_mfma_f32_16x16x32_bf16 v[118:121], v[172:175], v[188:191], v[118:121]
	v_mfma_f32_16x16x32_bf16 v[114:117], v[180:183], v[188:191], v[114:117]
	v_mfma_f32_16x16x32_bf16 v[102:105], v[172:175], v[196:199], v[102:105]
	v_mfma_f32_16x16x32_bf16 v[98:101], v[180:183], v[196:199], v[98:101]
	v_mfma_f32_16x16x32_bf16 v[86:89], v[172:175], v[208:211], v[86:89]
	v_mfma_f32_16x16x32_bf16 v[82:85], v[180:183], v[208:211], v[82:85]
	v_mfma_f32_16x16x32_bf16 v[70:73], v[172:175], v[216:219], v[70:73]
	v_mfma_f32_16x16x32_bf16 v[66:69], v[180:183], v[216:219], v[66:69]
	v_mfma_f32_16x16x32_bf16 v[118:121], v[176:179], v[192:195], v[118:121]
	v_mfma_f32_16x16x32_bf16 v[114:117], v[184:187], v[192:195], v[114:117]
	v_mfma_f32_16x16x32_bf16 v[102:105], v[176:179], v[200:203], v[102:105]
	v_mfma_f32_16x16x32_bf16 v[98:101], v[184:187], v[200:203], v[98:101]
	v_mfma_f32_16x16x32_bf16 v[86:89], v[176:179], v[212:215], v[86:89]
	v_mfma_f32_16x16x32_bf16 v[82:85], v[184:187], v[212:215], v[82:85]
	v_mfma_f32_16x16x32_bf16 v[70:73], v[176:179], v[220:223], v[70:73]
	v_mfma_f32_16x16x32_bf16 v[66:69], v[184:187], v[220:223], v[66:69]
	s_setprio 0
	s_barrier
; #define PG8_STAGE(bufoff, gbase, voff) do { _Pragma("unroll") for (int _i = 0; _i < 2; ++_i) \
;         __builtin_amdgcn_global_load_lds((const unsigned*)((const char*)(gbase) + (voff)[_i]), (PG8_LAS unsigned*)(lds + (bufoff) + ldsw + _i * 8192), 16, 0, 0); } while (0)
; #define PG8_LDA(dst, b, h) do { _Pragma("unroll") for (int m = 0; m < 4; ++m) _Pragma("unroll") for (int k = 0; k < 2; ++k) dst[m][k] = *(const PG8_LAS bf16x8*)(lds + PG8_SA(b, h) + aoff + m * 2048 + k * 1024); } while (0)
; #define PG8_MMA(ai, bj, At, Bt) do { __builtin_amdgcn_s_setprio(1); _Pragma("unroll") for (int m = 0; m < 4; ++m) _Pragma("unroll") for (int n = 0; n < 2; ++n) _Pragma("unroll") for (int k = 0; k < 2; ++k) \
;         acc[ai][bj][m][n] = __builtin_amdgcn_mfma_f32_16x16x32_bf16(Bt[n][k], At[m][k], acc[ai][bj][m][n], 0, 0, 0); __builtin_amdgcn_s_setprio(0); } while (0)
; #define PG8_WAIT_V(n) asm volatile("s_waitcnt vmcnt(" #n ")" ::: "memory")
; #define PG8_WAIT_L(n) asm volatile("s_waitcnt lgkmcnt(" #n ")" ::: "memory")
; #define PG8_BAR __builtin_amdgcn_s_barrier()
; #define PG8_SCHED __builtin_amdgcn_sched_barrier(0)
; template <class Epi, class Sched, bool ALIGN_EPI = false, bool SP2 = false>
; __device__ __forceinline__ void gemm_phase(PG8_LAS unsigned char* lds, const Gemm g, const Sched& S, const Epi& E) {
;     ...
;         for (int t = 0; t < nt; t += 2) {
;     ...
;             PG8_LDA(At, 1, 1); PG8_STAGE(PG8_SB(1, 0), b3, voffB); PG8_STAGE(PG8_SB(1, 1), b3 + hstep, voffB); PG8_STAGE(PG8_SA(1, 0), a3, voffA);
;             PG8_WAIT_V(8); PG8_WAIT_L(0); PG8_BAR; PG8_MMA(1, 0, At, B0); PG8_MMA(1, 1, At, B1); PG8_BAR; PG8_SCHED;
	s_add_i32 s44, s72, s47
	s_mov_b32 m0, s44
	ds_read_b128 v[188:191], v154 offset:49152
	ds_read_b128 v[192:195], v154 offset:50176
	ds_read_b128 v[196:199], v154 offset:51200
	ds_read_b128 v[200:203], v154 offset:52224
	ds_read_b128 v[208:211], v154 offset:53248
	ds_read_b128 v[212:215], v154 offset:54272
	ds_read_b128 v[216:219], v154 offset:55296
	ds_read_b128 v[220:223], v154 offset:56320
	s_add_u32 s98, s40, s12
	s_addc_u32 s99, s41, s13
	global_load_lds_dwordx4 v132, s[98:99]
	s_add_i32 m0, s44, 0x2000
	s_add_u32 s40, s40, 0x40080
	v_lshl_add_u64 v[148:149], v[204:205], 0, s[12:13]
	s_addc_u32 s41, s41, 0
	s_add_i32 s44, s73, s47
	global_load_lds_dwordx4 v[148:149], off
	s_mov_b32 m0, s44
	s_nop 0
	global_load_lds_dwordx4 v132, s[40:41]
	s_add_i32 m0, s44, 0x2000
	s_nop 0
	global_load_lds_dwordx4 v136, s[40:41]
	v_lshl_add_u64 v[148:149], v[224:225], 0, s[12:13]
	s_mov_b32 m0, s61
	s_nop 0
	global_load_lds_dwordx4 v[148:149], off
	v_lshl_add_u64 v[148:149], v[226:227], 0, s[12:13]
	s_mov_b32 m0, s62
	s_nop 0
	global_load_lds_dwordx4 v[148:149], off
	s_waitcnt vmcnt(8)
	s_waitcnt lgkmcnt(0)
	s_barrier
	s_setprio 1
	s_waitcnt lgkmcnt(0)
	v_mfma_f32_16x16x32_bf16 v[62:65], v[156:159], v[188:191], v[62:65]
	v_mfma_f32_16x16x32_bf16 v[58:61], v[164:167], v[188:191], v[58:61]
	v_mfma_f32_16x16x32_bf16 v[46:49], v[156:159], v[196:199], v[46:49]
	v_mfma_f32_16x16x32_bf16 v[42:45], v[164:167], v[196:199], v[42:45]
	v_mfma_f32_16x16x32_bf16 v[30:33], v[156:159], v[208:211], v[30:33]
	v_mfma_f32_16x16x32_bf16 v[26:29], v[164:167], v[208:211], v[26:29]
	v_mfma_f32_16x16x32_bf16 v[14:17], v[156:159], v[216:219], v[14:17]
	v_mfma_f32_16x16x32_bf16 v[10:13], v[164:167], v[216:219], v[10:13]
	v_mfma_f32_16x16x32_bf16 v[62:65], v[160:163], v[192:195], v[62:65]
	v_mfma_f32_16x16x32_bf16 v[58:61], v[168:171], v[192:195], v[58:61]
	v_mfma_f32_16x16x32_bf16 v[46:49], v[160:163], v[200:203], v[46:49]
	v_mfma_f32_16x16x32_bf16 v[42:45], v[168:171], v[200:203], v[42:45]
	v_mfma_f32_16x16x32_bf16 v[30:33], v[160:163], v[212:215], v[30:33]
	v_mfma_f32_16x16x32_bf16 v[26:29], v[168:171], v[212:215], v[26:29]
	v_mfma_f32_16x16x32_bf16 v[14:17], v[160:163], v[220:223], v[14:17]
	v_mfma_f32_16x16x32_bf16 v[10:13], v[168:171], v[220:223], v[10:13]
	s_setprio 0
	s_setprio 1
	v_mfma_f32_16x16x32_bf16 v[54:57], v[172:175], v[188:191], v[54:57]
	v_mfma_f32_16x16x32_bf16 v[50:53], v[180:183], v[188:191], v[50:53]
	v_mfma_f32_16x16x32_bf16 v[38:41], v[172:175], v[196:199], v[38:41]
	v_mfma_f32_16x16x32_bf16 v[34:37], v[180:183], v[196:199], v[34:37]
	v_mfma_f32_16x16x32_bf16 v[22:25], v[172:175], v[208:211], v[22:25]
	v_mfma_f32_16x16x32_bf16 v[18:21], v[180:183], v[208:211], v[18:21]
	v_mfma_f32_16x16x32_bf16 v[6:9], v[172:175], v[216:219], v[6:9]
	v_mfma_f32_16x16x32_bf16 v[2:5], v[180:183], v[216:219], v[2:5]
	v_mfma_f32_16x16x32_bf16 v[54:57], v[176:179], v[192:195], v[54:57]
	v_mfma_f32_16x16x32_bf16 v[50:53], v[184:187], v[192:195], v[50:53]
	v_mfma_f32_16x16x32_bf16 v[38:41], v[176:179], v[200:203], v[38:41]
	v_mfma_f32_16x16x32_bf16 v[34:37], v[184:187], v[200:203], v[34:37]
	v_mfma_f32_16x16x32_bf16 v[22:25], v[176:179], v[212:215], v[22:25]
	v_mfma_f32_16x16x32_bf16 v[18:21], v[184:187], v[212:215], v[18:21]
	v_mfma_f32_16x16x32_bf16 v[6:9], v[176:179], v[220:223], v[6:9]
	v_mfma_f32_16x16x32_bf16 v[2:5], v[184:187], v[220:223], v[2:5]
	s_setprio 0
	s_add_i32 s71, s71, 2
	s_add_u32 s30, s30, 0x100
	s_addc_u32 s31, s31, 0
	s_add_u32 s33, s33, 0x100
	s_addc_u32 s70, s70, 0
	s_cmp_gt_u32 s71, 13
	s_barrier

; #define PG8_STAGE(bufoff, gbase, voff) do { _Pragma("unroll") for (int _i = 0; _i < 2; ++_i) \
;         __builtin_amdgcn_global_load_lds((const unsigned*)((const char*)(gbase) + (voff)[_i]), (PG8_LAS unsigned*)(lds + (bufoff) + ldsw + _i * 8192), 16, 0, 0); } while (0)
; #define PG8_LDA(dst, b, h) do { _Pragma("unroll") for (int m = 0; m < 4; ++m) _Pragma("unroll") for (int k = 0; k < 2; ++k) dst[m][k] = *(const PG8_LAS bf16x8*)(lds + PG8_SA(b, h) + aoff + m * 2048 + k * 1024); } while (0)
; #define PG8_LDB(dst, b, h) do { _Pragma("unroll") for (int n = 0; n < 2; ++n) _Pragma("unroll") for (int k = 0; k < 2; ++k) dst[n][k] = *(const PG8_LAS bf16x8*)(lds + PG8_SB(b, h) + boff + n * 2048 + k * 1024); } while (0)
; #define PG8_MMA(ai, bj, At, Bt) do { __builtin_amdgcn_s_setprio(1); _Pragma("unroll") for (int m = 0; m < 4; ++m) _Pragma("unroll") for (int n = 0; n < 2; ++n) _Pragma("unroll") for (int k = 0; k < 2; ++k) \
;         acc[ai][bj][m][n] = __builtin_amdgcn_mfma_f32_16x16x32_bf16(Bt[n][k], At[m][k], acc[ai][bj][m][n], 0, 0, 0); __builtin_amdgcn_s_setprio(0); } while (0)
; #define PG8_WAIT_V(n) asm volatile("s_waitcnt vmcnt(" #n ")" ::: "memory")
; #define PG8_WAIT_L(n) asm volatile("s_waitcnt lgkmcnt(" #n ")" ::: "memory")
; template <class Epi, class Sched, bool ALIGN_EPI = false, bool SP2 = false>
; __device__ __forceinline__ void gemm_phase(PG8_LAS unsigned char* lds, const Gemm g, const Sched& S, const Epi& E) {
;     ...
;             const bool last = (t == nt - 2);
;             const char* a1 = cA + (size_t)(t + 1) * kstep;
;             const char* a2 = last ? nA : cA + (size_t)(t + 2) * kstep; const char* b2 = last ? nB : cB + (size_t)(t + 2) * kstep;
;             const char* a3 = a2 + kstep; const char* b3 = b2 + kstep;
;             if (last && has_next) S.a_ready(nxt);
;             if constexpr (SP2) {
;             PG8_LDB(B0, 0, 0); PG8_LDB(B1, 0, 1); PG8_SCHED; PG8_LDA(At, 0, 0); PG8_STAGE(PG8_SA(1, 1), a1 + hstep, voffA);
;             PG8_WAIT_V(8); PG8_WAIT_L(0); PG8_BAR; PG8_MMA(0, 0, At, B0); PG8_MMA(0, 1, At, B1); PG8_BAR; PG8_SCHED;
;             PG8_LDA(At, 0, 1); PG8_STAGE(PG8_SB(0, 0), b2, voffB); PG8_STAGE(PG8_SB(0, 1), b2 + hstep, voffB); PG8_STAGE(PG8_SA(0, 0), a2, voffA);
;             PG8_WAIT_V(8); PG8_WAIT_L(0); PG8_BAR; PG8_MMA(1, 0, At, B0); PG8_MMA(1, 1, At, B1); PG8_BAR; PG8_SCHED;
.LBB0_860:
	s_add_u32 s24, s24, 0xb0080
	s_addc_u32 s25, s25, 0
	s_add_u32 s51, s26, 0x100
	s_addc_u32 s52, s27, 0
	s_mov_b32 s53, -2
	ds_read_b128 v[146:149], v153
	ds_read_b128 v[156:159], v153 offset:1024
	ds_read_b128 v[160:163], v153 offset:2048
	ds_read_b128 v[164:167], v153 offset:3072
	ds_read_b128 v[168:171], v154
	ds_read_b128 v[172:175], v154 offset:1024
	ds_read_b128 v[176:179], v154 offset:2048
	ds_read_b128 v[180:183], v154 offset:3072
	s_add_u32 s26, s24, 0xfff50080
	s_addc_u32 s27, s25, -1
	s_cmp_eq_u32 s53, 40
	s_cselect_b32 s29, s5, s27
	s_cselect_b32 s28, s4, s26
	s_cselect_b32 s27, s23, s52
	s_cselect_b32 s26, s22, s51
	v_lshl_add_u64 v[150:151], s[24:25], 0, v[138:139]
	s_add_i32 m0, s33, 0xc000
	ds_read_b128 v[184:187], v155
	ds_read_b128 v[188:191], v155 offset:1024
	ds_read_b128 v[192:195], v155 offset:2048
	ds_read_b128 v[196:199], v155 offset:3072
	ds_read_b128 v[200:203], v155 offset:4096
	ds_read_b128 v[204:207], v155 offset:5120
	ds_read_b128 v[208:211], v155 offset:6144
	ds_read_b128 v[212:215], v155 offset:7168
	global_load_lds_dwordx4 v[150:151], off
	v_lshl_add_u64 v[150:151], s[24:25], 0, v[140:141]
	s_add_i32 m0, s33, 0xe000
	s_nop 0
	global_load_lds_dwordx4 v[150:151], off
	s_waitcnt vmcnt(8)
	s_waitcnt lgkmcnt(0)
	s_barrier
	s_setprio 1
	s_waitcnt lgkmcnt(0)
	v_mfma_f32_16x16x32_bf16 v[124:127], v[146:149], v[184:187], 0
	v_mfma_f32_16x16x32_bf16 v[120:123], v[160:163], v[184:187], 0
	v_mfma_f32_16x16x32_bf16 v[108:111], v[146:149], v[192:195], 0
	v_mfma_f32_16x16x32_bf16 v[104:107], v[160:163], v[192:195], 0
	v_mfma_f32_16x16x32_bf16 v[92:95], v[146:149], v[200:203], 0
	v_mfma_f32_16x16x32_bf16 v[88:91], v[160:163], v[200:203], 0
	v_mfma_f32_16x16x32_bf16 v[76:79], v[146:149], v[208:211], 0
	v_mfma_f32_16x16x32_bf16 v[72:75], v[160:163], v[208:211], 0
	v_mfma_f32_16x16x32_bf16 v[124:127], v[156:159], v[188:191], v[124:127]
	v_mfma_f32_16x16x32_bf16 v[120:123], v[164:167], v[188:191], v[120:123]
	v_mfma_f32_16x16x32_bf16 v[108:111], v[156:159], v[196:199], v[108:111]
	v_mfma_f32_16x16x32_bf16 v[104:107], v[164:167], v[196:199], v[104:107]
	v_mfma_f32_16x16x32_bf16 v[92:95], v[156:159], v[204:207], v[92:95]
	v_mfma_f32_16x16x32_bf16 v[88:91], v[164:167], v[204:207], v[88:91]
	v_mfma_f32_16x16x32_bf16 v[76:79], v[156:159], v[212:215], v[76:79]
	v_mfma_f32_16x16x32_bf16 v[72:75], v[164:167], v[212:215], v[72:75]
	s_setprio 0
	s_setprio 1
	v_mfma_f32_16x16x32_bf16 v[116:119], v[168:171], v[184:187], 0
	v_mfma_f32_16x16x32_bf16 v[112:115], v[176:179], v[184:187], 0
	v_mfma_f32_16x16x32_bf16 v[100:103], v[168:171], v[192:195], 0
	v_mfma_f32_16x16x32_bf16 v[96:99], v[176:179], v[192:195], 0
	v_mfma_f32_16x16x32_bf16 v[84:87], v[168:171], v[200:203], 0
	v_mfma_f32_16x16x32_bf16 v[80:83], v[176:179], v[200:203], 0
	v_mfma_f32_16x16x32_bf16 v[68:71], v[168:171], v[208:211], 0
	v_mfma_f32_16x16x32_bf16 v[64:67], v[176:179], v[208:211], 0
	v_mfma_f32_16x16x32_bf16 v[116:119], v[172:175], v[188:191], v[116:119]
	v_mfma_f32_16x16x32_bf16 v[112:115], v[180:183], v[188:191], v[112:115]
	v_mfma_f32_16x16x32_bf16 v[100:103], v[172:175], v[196:199], v[100:103]
	v_mfma_f32_16x16x32_bf16 v[96:99], v[180:183], v[196:199], v[96:99]
	v_mfma_f32_16x16x32_bf16 v[84:87], v[172:175], v[204:207], v[84:87]
	v_mfma_f32_16x16x32_bf16 v[80:83], v[180:183], v[204:207], v[80:83]
	v_mfma_f32_16x16x32_bf16 v[68:71], v[172:175], v[212:215], v[68:71]
	v_mfma_f32_16x16x32_bf16 v[64:67], v[180:183], v[212:215], v[64:67]
	s_setprio 0
	s_barrier
	s_add_i32 s56, s45, s31
	s_mov_b32 m0, s56
	ds_read_b128 v[184:187], v155 offset:16384
	ds_read_b128 v[188:191], v155 offset:17408
	ds_read_b128 v[192:195], v155 offset:18432
	ds_read_b128 v[196:199], v155 offset:19456
	ds_read_b128 v[200:203], v155 offset:20480
	ds_read_b128 v[204:207], v155 offset:21504
	ds_read_b128 v[208:211], v155 offset:22528
	ds_read_b128 v[212:215], v155 offset:23552
	global_load_lds_dwordx4 v130, s[26:27]
	s_add_i32 m0, s56, 0x2000
	s_add_u32 s56, s26, 0xb0000
	v_lshl_add_u64 v[216:217], s[26:27], 0, v[134:135]
	s_addc_u32 s57, s27, 0
	s_add_i32 s58, s46, s31
	global_load_lds_dwordx4 v134, s[26:27]
	s_mov_b32 m0, s58
	v_lshl_add_u64 v[220:221], s[28:29], 0, v[132:133]
	global_load_lds_dwordx4 v130, s[56:57]
	s_add_i32 m0, s58, 0x2000
	s_nop 0
	global_load_lds_dwordx4 v134, s[56:57]
	v_lshl_add_u64 v[218:219], s[28:29], 0, v[128:129]
	s_mov_b32 m0, s33
	s_nop 0
	global_load_lds_dwordx4 v128, s[28:29]
	s_mov_b32 m0, s36
	s_nop 0
	global_load_lds_dwordx4 v132, s[28:29]
	s_waitcnt vmcnt(8)
	s_waitcnt lgkmcnt(0)
	s_barrier
; #define PG8_STAGE(bufoff, gbase, voff) do { _Pragma("unroll") for (int _i = 0; _i < 2; ++_i) \
;         __builtin_amdgcn_global_load_lds((const unsigned*)((const char*)(gbase) + (voff)[_i]), (PG8_LAS unsigned*)(lds + (bufoff) + ldsw + _i * 8192), 16, 0, 0); } while (0)
; #define PG8_LDA(dst, b, h) do { _Pragma("unroll") for (int m = 0; m < 4; ++m) _Pragma("unroll") for (int k = 0; k < 2; ++k) dst[m][k] = *(const PG8_LAS bf16x8*)(lds + PG8_SA(b, h) + aoff + m * 2048 + k * 1024); } while (0)
; #define PG8_LDB(dst, b, h) do { _Pragma("unroll") for (int n = 0; n < 2; ++n) _Pragma("unroll") for (int k = 0; k < 2; ++k) dst[n][k] = *(const PG8_LAS bf16x8*)(lds + PG8_SB(b, h) + boff + n * 2048 + k * 1024); } while (0)
; #define PG8_MMA(ai, bj, At, Bt) do { __builtin_amdgcn_s_setprio(1); _Pragma("unroll") for (int m = 0; m < 4; ++m) _Pragma("unroll") for (int n = 0; n < 2; ++n) _Pragma("unroll") for (int k = 0; k < 2; ++k) \
;         acc[ai][bj][m][n] = __builtin_amdgcn_mfma_f32_16x16x32_bf16(Bt[n][k], At[m][k], acc[ai][bj][m][n], 0, 0, 0); __builtin_amdgcn_s_setprio(0); } while (0)
; #define PG8_WAIT_V(n) asm volatile("s_waitcnt vmcnt(" #n ")" ::: "memory")
; #define PG8_WAIT_L(n) asm volatile("s_waitcnt lgkmcnt(" #n ")" ::: "memory")
; #define PG8_BAR __builtin_amdgcn_s_barrier()
; #define PG8_SCHED __builtin_amdgcn_sched_barrier(0)
; template <class Epi, class Sched, bool ALIGN_EPI = false, bool SP2 = false>
; __device__ __forceinline__ void gemm_phase(PG8_LAS unsigned char* lds, const Gemm g, const Sched& S, const Epi& E) {
;     ...
;             PG8_WAIT_V(8); PG8_WAIT_L(0); PG8_BAR; PG8_MMA(1, 0, At, B0); PG8_MMA(1, 1, At, B1); PG8_BAR; PG8_SCHED;
;             PG8_LDB(B0, 1, 0); PG8_LDB(B1, 1, 1); PG8_SCHED; PG8_LDA(At, 1, 0); PG8_STAGE(PG8_SA(0, 1), a2 + hstep, voffA);
;             PG8_WAIT_V(8); PG8_WAIT_L(0); PG8_BAR; PG8_MMA(0, 0, At, B0); PG8_MMA(0, 1, At, B1); PG8_BAR; PG8_SCHED;
	s_setprio 1
	s_waitcnt lgkmcnt(0)
	v_mfma_f32_16x16x32_bf16 v[60:63], v[146:149], v[184:187], 0
	v_mfma_f32_16x16x32_bf16 v[56:59], v[160:163], v[184:187], 0
	v_mfma_f32_16x16x32_bf16 v[44:47], v[146:149], v[192:195], 0
	v_mfma_f32_16x16x32_bf16 v[40:43], v[160:163], v[192:195], 0
	v_mfma_f32_16x16x32_bf16 v[28:31], v[146:149], v[200:203], 0
	v_mfma_f32_16x16x32_bf16 v[24:27], v[160:163], v[200:203], 0
	v_mfma_f32_16x16x32_bf16 v[12:15], v[146:149], v[208:211], 0
	v_mfma_f32_16x16x32_bf16 v[8:11], v[160:163], v[208:211], 0
	v_mfma_f32_16x16x32_bf16 v[60:63], v[156:159], v[188:191], v[60:63]
	v_mfma_f32_16x16x32_bf16 v[56:59], v[164:167], v[188:191], v[56:59]
	v_mfma_f32_16x16x32_bf16 v[44:47], v[156:159], v[196:199], v[44:47]
	v_mfma_f32_16x16x32_bf16 v[40:43], v[164:167], v[196:199], v[40:43]
	v_mfma_f32_16x16x32_bf16 v[28:31], v[156:159], v[204:207], v[28:31]
	v_mfma_f32_16x16x32_bf16 v[24:27], v[164:167], v[204:207], v[24:27]
	v_mfma_f32_16x16x32_bf16 v[12:15], v[156:159], v[212:215], v[12:15]
	v_mfma_f32_16x16x32_bf16 v[8:11], v[164:167], v[212:215], v[8:11]
	s_setprio 0
	s_setprio 1
	v_mfma_f32_16x16x32_bf16 v[52:55], v[168:171], v[184:187], 0
	v_mfma_f32_16x16x32_bf16 v[48:51], v[176:179], v[184:187], 0
	v_mfma_f32_16x16x32_bf16 v[36:39], v[168:171], v[192:195], 0
	v_mfma_f32_16x16x32_bf16 v[32:35], v[176:179], v[192:195], 0
	v_mfma_f32_16x16x32_bf16 v[20:23], v[168:171], v[200:203], 0
	v_mfma_f32_16x16x32_bf16 v[16:19], v[176:179], v[200:203], 0
	v_mfma_f32_16x16x32_bf16 v[4:7], v[168:171], v[208:211], 0
	v_mfma_f32_16x16x32_bf16 v[0:3], v[176:179], v[208:211], 0
	v_mfma_f32_16x16x32_bf16 v[52:55], v[172:175], v[188:191], v[52:55]
	v_mfma_f32_16x16x32_bf16 v[48:51], v[180:183], v[188:191], v[48:51]
	v_mfma_f32_16x16x32_bf16 v[36:39], v[172:175], v[196:199], v[36:39]
	v_mfma_f32_16x16x32_bf16 v[32:35], v[180:183], v[196:199], v[32:35]
	v_mfma_f32_16x16x32_bf16 v[20:23], v[172:175], v[204:207], v[20:23]
	v_mfma_f32_16x16x32_bf16 v[16:19], v[180:183], v[204:207], v[16:19]
	v_mfma_f32_16x16x32_bf16 v[4:7], v[172:175], v[212:215], v[4:7]
	v_mfma_f32_16x16x32_bf16 v[0:3], v[180:183], v[212:215], v[0:3]
	s_setprio 0
	s_barrier
	s_add_i32 s56, 0, 0x18000
	s_add_i32 s57, 0, 0x1c000
	v_add_u32_e32 v164, s56, v152
	v_add_u32_e32 v180, s57, v152
	ds_read_b128 v[146:149], v164
	ds_read_b128 v[156:159], v164 offset:1024
	ds_read_b128 v[160:163], v164 offset:2048
	ds_read_b128 v[164:167], v164 offset:3072
	ds_read_b128 v[168:171], v180
	ds_read_b128 v[172:175], v180 offset:1024
	ds_read_b128 v[176:179], v180 offset:2048
	ds_read_b128 v[180:183], v180 offset:3072
	s_add_u32 s28, s28, 0xb0000
	s_addc_u32 s29, s29, 0
	s_mov_b32 m0, s37
	ds_read_b128 v[184:187], v155 offset:32768
	ds_read_b128 v[188:191], v155 offset:33792
	ds_read_b128 v[192:195], v155 offset:34816
	ds_read_b128 v[196:199], v155 offset:35840
	ds_read_b128 v[200:203], v155 offset:36864
	ds_read_b128 v[204:207], v155 offset:37888
	ds_read_b128 v[208:211], v155 offset:38912
	ds_read_b128 v[212:215], v155 offset:39936
	global_load_lds_dwordx4 v128, s[28:29]
	s_mov_b32 m0, s38
	s_nop 0
	global_load_lds_dwordx4 v132, s[28:29]
	s_waitcnt vmcnt(8)
	s_waitcnt lgkmcnt(0)
	s_barrier
	s_setprio 1
	s_waitcnt lgkmcnt(0)
	v_mfma_f32_16x16x32_bf16 v[124:127], v[146:149], v[184:187], v[124:127]
	v_mfma_f32_16x16x32_bf16 v[120:123], v[160:163], v[184:187], v[120:123]
	v_mfma_f32_16x16x32_bf16 v[108:111], v[146:149], v[192:195], v[108:111]
	v_mfma_f32_16x16x32_bf16 v[104:107], v[160:163], v[192:195], v[104:107]
	v_mfma_f32_16x16x32_bf16 v[92:95], v[146:149], v[200:203], v[92:95]
	v_mfma_f32_16x16x32_bf16 v[88:91], v[160:163], v[200:203], v[88:91]
	v_mfma_f32_16x16x32_bf16 v[76:79], v[146:149], v[208:211], v[76:79]
	v_mfma_f32_16x16x32_bf16 v[72:75], v[160:163], v[208:211], v[72:75]
	v_mfma_f32_16x16x32_bf16 v[124:127], v[156:159], v[188:191], v[124:127]
	v_mfma_f32_16x16x32_bf16 v[120:123], v[164:167], v[188:191], v[120:123]
	v_mfma_f32_16x16x32_bf16 v[108:111], v[156:159], v[196:199], v[108:111]
	v_mfma_f32_16x16x32_bf16 v[104:107], v[164:167], v[196:199], v[104:107]
	v_mfma_f32_16x16x32_bf16 v[92:95], v[156:159], v[204:207], v[92:95]
	v_mfma_f32_16x16x32_bf16 v[88:91], v[164:167], v[204:207], v[88:91]
	v_mfma_f32_16x16x32_bf16 v[76:79], v[156:159], v[212:215], v[76:79]
	v_mfma_f32_16x16x32_bf16 v[72:75], v[164:167], v[212:215], v[72:75]
	s_setprio 0
	s_setprio 1
	v_mfma_f32_16x16x32_bf16 v[116:119], v[168:171], v[184:187], v[116:119]
	v_mfma_f32_16x16x32_bf16 v[112:115], v[176:179], v[184:187], v[112:115]
	v_mfma_f32_16x16x32_bf16 v[100:103], v[168:171], v[192:195], v[100:103]
	v_mfma_f32_16x16x32_bf16 v[96:99], v[176:179], v[192:195], v[96:99]
	v_mfma_f32_16x16x32_bf16 v[84:87], v[168:171], v[200:203], v[84:87]
	v_mfma_f32_16x16x32_bf16 v[80:83], v[176:179], v[200:203], v[80:83]
	v_mfma_f32_16x16x32_bf16 v[68:71], v[168:171], v[208:211], v[68:71]
	v_mfma_f32_16x16x32_bf16 v[64:67], v[176:179], v[208:211], v[64:67]
	v_mfma_f32_16x16x32_bf16 v[116:119], v[172:175], v[188:191], v[116:119]
	v_mfma_f32_16x16x32_bf16 v[112:115], v[180:183], v[188:191], v[112:115]
	v_mfma_f32_16x16x32_bf16 v[100:103], v[172:175], v[196:199], v[100:103]
	v_mfma_f32_16x16x32_bf16 v[96:99], v[180:183], v[196:199], v[96:99]
	v_mfma_f32_16x16x32_bf16 v[84:87], v[172:175], v[204:207], v[84:87]
	v_mfma_f32_16x16x32_bf16 v[80:83], v[180:183], v[204:207], v[80:83]
	v_mfma_f32_16x16x32_bf16 v[68:71], v[172:175], v[212:215], v[68:71]
	v_mfma_f32_16x16x32_bf16 v[64:67], v[180:183], v[212:215], v[64:67]
	s_setprio 0
	s_barrier
; #define PG8_STAGE(bufoff, gbase, voff) do { _Pragma("unroll") for (int _i = 0; _i < 2; ++_i) \
;         __builtin_amdgcn_global_load_lds((const unsigned*)((const char*)(gbase) + (voff)[_i]), (PG8_LAS unsigned*)(lds + (bufoff) + ldsw + _i * 8192), 16, 0, 0); } while (0)
; #define PG8_LDA(dst, b, h) do { _Pragma("unroll") for (int m = 0; m < 4; ++m) _Pragma("unroll") for (int k = 0; k < 2; ++k) dst[m][k] = *(const PG8_LAS bf16x8*)(lds + PG8_SA(b, h) + aoff + m * 2048 + k * 1024); } while (0)
; #define PG8_MMA(ai, bj, At, Bt) do { __builtin_amdgcn_s_setprio(1); _Pragma("unroll") for (int m = 0; m < 4; ++m) _Pragma("unroll") for (int n = 0; n < 2; ++n) _Pragma("unroll") for (int k = 0; k < 2; ++k) \
;         acc[ai][bj][m][n] = __builtin_amdgcn_mfma_f32_16x16x32_bf16(Bt[n][k], At[m][k], acc[ai][bj][m][n], 0, 0, 0); __builtin_amdgcn_s_setprio(0); } while (0)
; #define PG8_WAIT_V(n) asm volatile("s_waitcnt vmcnt(" #n ")" ::: "memory")
; #define PG8_WAIT_L(n) asm volatile("s_waitcnt lgkmcnt(" #n ")" ::: "memory")
; #define PG8_BAR __builtin_amdgcn_s_barrier()
; #define PG8_SCHED __builtin_amdgcn_sched_barrier(0)
; template <class Epi, class Sched, bool ALIGN_EPI = false, bool SP2 = false>
; __device__ __forceinline__ void gemm_phase(PG8_LAS unsigned char* lds, const Gemm g, const Sched& S, const Epi& E) {
;     ...
;         for (int t = 0; t < nt; t += 2) {
;     ...
;             PG8_LDA(At, 1, 1); PG8_STAGE(PG8_SB(1, 0), b3, voffB); PG8_STAGE(PG8_SB(1, 1), b3 + hstep, voffB); PG8_STAGE(PG8_SA(1, 0), a3, voffA);
;             PG8_WAIT_V(8); PG8_WAIT_L(0); PG8_BAR; PG8_MMA(1, 0, At, B0); PG8_MMA(1, 1, At, B1); PG8_BAR; PG8_SCHED;
	s_add_i32 s28, s56, s31
	s_mov_b32 m0, s28
	ds_read_b128 v[184:187], v155 offset:49152
	ds_read_b128 v[188:191], v155 offset:50176
	ds_read_b128 v[192:195], v155 offset:51200
	ds_read_b128 v[196:199], v155 offset:52224
	ds_read_b128 v[200:203], v155 offset:53248
	ds_read_b128 v[204:207], v155 offset:54272
	ds_read_b128 v[208:211], v155 offset:55296
	ds_read_b128 v[212:215], v155 offset:56320
	s_add_u32 s98, s26, s10
	s_addc_u32 s99, s27, s11
	global_load_lds_dwordx4 v130, s[98:99]
	s_add_i32 m0, s28, 0x2000
	s_add_u32 s26, s26, 0xb0080
	v_lshl_add_u64 v[150:151], v[216:217], 0, s[10:11]
	s_addc_u32 s27, s27, 0
	s_add_i32 s28, s57, s31
	global_load_lds_dwordx4 v[150:151], off
	s_mov_b32 m0, s28
	s_nop 0
	global_load_lds_dwordx4 v130, s[26:27]
	s_add_i32 m0, s28, 0x2000
	s_nop 0
	global_load_lds_dwordx4 v134, s[26:27]
	v_lshl_add_u64 v[150:151], v[218:219], 0, s[10:11]
	s_mov_b32 m0, s40
	s_nop 0
	global_load_lds_dwordx4 v[150:151], off
	v_lshl_add_u64 v[150:151], v[220:221], 0, s[10:11]
	s_mov_b32 m0, s41
	s_nop 0
	global_load_lds_dwordx4 v[150:151], off
	s_waitcnt vmcnt(8)
	s_waitcnt lgkmcnt(0)
	s_barrier
	s_setprio 1
	s_waitcnt lgkmcnt(0)
	v_mfma_f32_16x16x32_bf16 v[60:63], v[146:149], v[184:187], v[60:63]
	v_mfma_f32_16x16x32_bf16 v[56:59], v[160:163], v[184:187], v[56:59]
	v_mfma_f32_16x16x32_bf16 v[44:47], v[146:149], v[192:195], v[44:47]
	v_mfma_f32_16x16x32_bf16 v[40:43], v[160:163], v[192:195], v[40:43]
	v_mfma_f32_16x16x32_bf16 v[28:31], v[146:149], v[200:203], v[28:31]
	v_mfma_f32_16x16x32_bf16 v[24:27], v[160:163], v[200:203], v[24:27]
	v_mfma_f32_16x16x32_bf16 v[12:15], v[146:149], v[208:211], v[12:15]
	v_mfma_f32_16x16x32_bf16 v[8:11], v[160:163], v[208:211], v[8:11]
	v_mfma_f32_16x16x32_bf16 v[60:63], v[156:159], v[188:191], v[60:63]
	v_mfma_f32_16x16x32_bf16 v[56:59], v[164:167], v[188:191], v[56:59]
	v_mfma_f32_16x16x32_bf16 v[44:47], v[156:159], v[196:199], v[44:47]
	v_mfma_f32_16x16x32_bf16 v[40:43], v[164:167], v[196:199], v[40:43]
	v_mfma_f32_16x16x32_bf16 v[28:31], v[156:159], v[204:207], v[28:31]
	v_mfma_f32_16x16x32_bf16 v[24:27], v[164:167], v[204:207], v[24:27]
	v_mfma_f32_16x16x32_bf16 v[12:15], v[156:159], v[212:215], v[12:15]
	v_mfma_f32_16x16x32_bf16 v[8:11], v[164:167], v[212:215], v[8:11]
	s_setprio 0
	s_setprio 1
	v_mfma_f32_16x16x32_bf16 v[52:55], v[168:171], v[184:187], v[52:55]
	v_mfma_f32_16x16x32_bf16 v[48:51], v[176:179], v[184:187], v[48:51]
	v_mfma_f32_16x16x32_bf16 v[36:39], v[168:171], v[192:195], v[36:39]
	v_mfma_f32_16x16x32_bf16 v[32:35], v[176:179], v[192:195], v[32:35]
	v_mfma_f32_16x16x32_bf16 v[20:23], v[168:171], v[200:203], v[20:23]
	v_mfma_f32_16x16x32_bf16 v[16:19], v[176:179], v[200:203], v[16:19]
	v_mfma_f32_16x16x32_bf16 v[4:7], v[168:171], v[208:211], v[4:7]
	v_mfma_f32_16x16x32_bf16 v[0:3], v[176:179], v[208:211], v[0:3]
	v_mfma_f32_16x16x32_bf16 v[52:55], v[172:175], v[188:191], v[52:55]
	v_mfma_f32_16x16x32_bf16 v[48:51], v[180:183], v[188:191], v[48:51]
	v_mfma_f32_16x16x32_bf16 v[36:39], v[172:175], v[196:199], v[36:39]
	v_mfma_f32_16x16x32_bf16 v[32:35], v[180:183], v[196:199], v[32:35]
	v_mfma_f32_16x16x32_bf16 v[20:23], v[172:175], v[204:207], v[20:23]
	v_mfma_f32_16x16x32_bf16 v[16:19], v[180:183], v[204:207], v[16:19]
	v_mfma_f32_16x16x32_bf16 v[4:7], v[172:175], v[212:215], v[4:7]
	v_mfma_f32_16x16x32_bf16 v[0:3], v[180:183], v[212:215], v[0:3]
	s_setprio 0
	s_add_i32 s53, s53, 2
	s_add_u32 s24, s24, 0x100
	s_addc_u32 s25, s25, 0
	s_add_u32 s51, s51, 0x100
	s_addc_u32 s52, s52, 0
	s_cmp_gt_u32 s53, 41
	s_barrier
